# P10: ids/partials/weights kept in LDS, gathers streamed in two half-buffers across tokens (next token prefetched behind current)
# speedup vs baseline: 1.0436x; 1.0436x over previous
.LBB0_289:
	s_nop 0
	v_readlane_b32 s0, v254, 20
	v_readlane_b32 s1, v254, 21
	s_and_b64 vcc, exec, s[0:1]
	s_cbranch_vccz .LBB0_310
	s_sub_i32 s2, s28, 12
	s_mul_i32 s2, s2, 0x199a
	s_lshr_b32 s2, s2, 16
	s_movk_i32 s9, 0x2200
	s_cmp_eq_u32 s2, 3
	s_cselect_b32 s3, 1, 0
	s_cselect_b32 s9, 0x2000, s9
	v_mov_b32_e32 v0, 0x120a0
	ds_read_b64 v[0:1], v0
	v_and_b32_e32 v2, 63, v211
	v_lshrrev_b32_e32 v3, 6, v211
	v_and_b32_e32 v4, 7, v2
	v_lshrrev_b32_e32 v5, 3, v2
	s_waitcnt lgkmcnt(0)
	v_readfirstlane_b32 s4, v0
	v_readfirstlane_b32 s5, v1
	v_readfirstlane_b32 s15, v3
	s_load_dwordx2 s[6:7], s[4:5], 0xc0
	s_load_dwordx2 s[10:11], s[4:5], 0xb8
	v_lshlrev_b32_e32 v200, 4, v4
	v_lshlrev_b32_e32 v201, 5, v4
	v_lshlrev_b32_e32 v202, 6, v5
	v_lshlrev_b32_e32 v203, 3, v2
	v_lshlrev_b32_e32 v204, 6, v4
	v_lshl_add_u32 v204, v5, 3, v204
	v_lshlrev_b32_e32 v205, 6, v2
	v_lshlrev_b32_e32 v206, 5, v2
	v_mul_u32_u24_e32 v10, 0x4400, v3
	v_add_u32_e32 v207, v10, v202
	v_add_u32_e32 v198, v10, v203
	v_add_u32_e32 v198, 0x2200, v198
	v_add_u32_e32 v197, 0x2200, v207
	v_and_b32_e32 v6, 4, v2
	v_cmp_ne_u32_e64 s[36:37], 0, v6
	v_and_b32_e32 v7, 2, v2
	v_cmp_ne_u32_e64 s[38:39], 0, v7
	v_and_b32_e32 v8, 1, v2
	v_cmp_ne_u32_e64 s[16:17], 0, v8
	v_and_b32_e32 v9, 8, v2
	v_cmp_ne_u32_e64 s[18:19], 0, v9
	v_readlane_b32 s101, v252, 0
	s_waitcnt lgkmcnt(0)
	s_mov_b32 s12, 0
	s_mov_b32 s14, s101
.Lq_cnt_1:
	s_cmp_ge_i32 s14, s9
	s_cbranch_scc1 .Lq_cnte_2
	s_add_i32 s12, s12, 1
	s_add_i32 s14, s14, s26
	s_branch .Lq_cnt_1
.Lq_cnte_2:
	s_cmp_eq_u32 s12, 0
	s_cbranch_scc1 .Lq_done
	s_min_u32 s12, s12, 17
	s_mov_b32 s14, s101
	s_lshl_b32 s20, s14, 2
	s_add_u32 s20, s20, s15
	s_lshl_b32 s0, s20, 9
	s_add_u32 s0, s0, 0x28600000
	v_add_u32_e32 v120, s0, v203
	global_load_dwordx2 v[40:41], v120, s[6:7]
	s_add_i32 s14, s14, s26
	s_cmp_le_u32 s12, 1
	s_cbranch_scc1 .Lq_ldw
	s_lshl_b32 s20, s14, 2
	s_add_u32 s20, s20, s15
	s_lshl_b32 s0, s20, 9
	s_add_u32 s0, s0, 0x28600000
	v_add_u32_e32 v120, s0, v203
	global_load_dwordx2 v[42:43], v120, s[6:7]
	s_add_i32 s14, s14, s26
	s_cmp_le_u32 s12, 2
	s_cbranch_scc1 .Lq_ldw
	s_lshl_b32 s20, s14, 2
	s_add_u32 s20, s20, s15
	s_lshl_b32 s0, s20, 9
	s_add_u32 s0, s0, 0x28600000
	v_add_u32_e32 v120, s0, v203
	global_load_dwordx2 v[44:45], v120, s[6:7]
	s_add_i32 s14, s14, s26
	s_cmp_le_u32 s12, 3
	s_cbranch_scc1 .Lq_ldw
	s_lshl_b32 s20, s14, 2
	s_add_u32 s20, s20, s15
	s_lshl_b32 s0, s20, 9
	s_add_u32 s0, s0, 0x28600000
	v_add_u32_e32 v120, s0, v203
	global_load_dwordx2 v[46:47], v120, s[6:7]
	s_add_i32 s14, s14, s26
	s_cmp_le_u32 s12, 4
	s_cbranch_scc1 .Lq_ldw
	s_lshl_b32 s20, s14, 2
	s_add_u32 s20, s20, s15
	s_lshl_b32 s0, s20, 9
	s_add_u32 s0, s0, 0x28600000
	v_add_u32_e32 v120, s0, v203
	global_load_dwordx2 v[48:49], v120, s[6:7]
	s_add_i32 s14, s14, s26
	s_cmp_le_u32 s12, 5
	s_cbranch_scc1 .Lq_ldw
	s_lshl_b32 s20, s14, 2
	s_add_u32 s20, s20, s15
	s_lshl_b32 s0, s20, 9
	s_add_u32 s0, s0, 0x28600000
	v_add_u32_e32 v120, s0, v203
	global_load_dwordx2 v[50:51], v120, s[6:7]
	s_add_i32 s14, s14, s26
	s_cmp_le_u32 s12, 6
	s_cbranch_scc1 .Lq_ldw
	s_lshl_b32 s20, s14, 2
	s_add_u32 s20, s20, s15
	s_lshl_b32 s0, s20, 9
	s_add_u32 s0, s0, 0x28600000
	v_add_u32_e32 v120, s0, v203
	global_load_dwordx2 v[52:53], v120, s[6:7]
	s_add_i32 s14, s14, s26
	s_cmp_le_u32 s12, 7
	s_cbranch_scc1 .Lq_ldw
	s_lshl_b32 s20, s14, 2
	s_add_u32 s20, s20, s15
	s_lshl_b32 s0, s20, 9
	s_add_u32 s0, s0, 0x28600000
	v_add_u32_e32 v120, s0, v203
	global_load_dwordx2 v[54:55], v120, s[6:7]
	s_add_i32 s14, s14, s26
	s_cmp_le_u32 s12, 8
	s_cbranch_scc1 .Lq_ldw
	s_lshl_b32 s20, s14, 2
	s_add_u32 s20, s20, s15
	s_lshl_b32 s0, s20, 9
	s_add_u32 s0, s0, 0x28600000
	v_add_u32_e32 v120, s0, v203
	global_load_dwordx2 v[56:57], v120, s[6:7]
	s_add_i32 s14, s14, s26
	s_cmp_le_u32 s12, 9
	s_cbranch_scc1 .Lq_ldw
	s_lshl_b32 s20, s14, 2
	s_add_u32 s20, s20, s15
	s_lshl_b32 s0, s20, 9
	s_add_u32 s0, s0, 0x28600000
	v_add_u32_e32 v120, s0, v203
	global_load_dwordx2 v[58:59], v120, s[6:7]
	s_add_i32 s14, s14, s26
	s_cmp_le_u32 s12, 10
	s_cbranch_scc1 .Lq_ldw
	s_lshl_b32 s20, s14, 2
	s_add_u32 s20, s20, s15
	s_lshl_b32 s0, s20, 9
	s_add_u32 s0, s0, 0x28600000
	v_add_u32_e32 v120, s0, v203
	global_load_dwordx2 v[60:61], v120, s[6:7]
	s_add_i32 s14, s14, s26
	s_cmp_le_u32 s12, 11
	s_cbranch_scc1 .Lq_ldw
	s_lshl_b32 s20, s14, 2
	s_add_u32 s20, s20, s15
	s_lshl_b32 s0, s20, 9
	s_add_u32 s0, s0, 0x28600000
	v_add_u32_e32 v120, s0, v203
	global_load_dwordx2 v[62:63], v120, s[6:7]
	s_add_i32 s14, s14, s26
	s_cmp_le_u32 s12, 12
	s_cbranch_scc1 .Lq_ldw
	s_lshl_b32 s20, s14, 2
	s_add_u32 s20, s20, s15
	s_lshl_b32 s0, s20, 9
	s_add_u32 s0, s0, 0x28600000
	v_add_u32_e32 v120, s0, v203
	global_load_dwordx2 v[64:65], v120, s[6:7]
	s_add_i32 s14, s14, s26
	s_cmp_le_u32 s12, 13
	s_cbranch_scc1 .Lq_ldw
	s_lshl_b32 s20, s14, 2
	s_add_u32 s20, s20, s15
	s_lshl_b32 s0, s20, 9
	s_add_u32 s0, s0, 0x28600000
	v_add_u32_e32 v120, s0, v203
	global_load_dwordx2 v[66:67], v120, s[6:7]
	s_add_i32 s14, s14, s26
	s_cmp_le_u32 s12, 14
	s_cbranch_scc1 .Lq_ldw
	s_lshl_b32 s20, s14, 2
	s_add_u32 s20, s20, s15
	s_lshl_b32 s0, s20, 9
	s_add_u32 s0, s0, 0x28600000
	v_add_u32_e32 v120, s0, v203
	global_load_dwordx2 v[68:69], v120, s[6:7]
	s_add_i32 s14, s14, s26
	s_cmp_le_u32 s12, 15
	s_cbranch_scc1 .Lq_ldw
	s_lshl_b32 s20, s14, 2
	s_add_u32 s20, s20, s15
	s_lshl_b32 s0, s20, 9
	s_add_u32 s0, s0, 0x28600000
	v_add_u32_e32 v120, s0, v203
	global_load_dwordx2 v[70:71], v120, s[6:7]
	s_add_i32 s14, s14, s26
	s_cmp_le_u32 s12, 16
	s_cbranch_scc1 .Lq_ldw
	s_lshl_b32 s20, s14, 2
	s_add_u32 s20, s20, s15
	s_lshl_b32 s0, s20, 9
	s_add_u32 s0, s0, 0x28600000
	v_add_u32_e32 v120, s0, v203
	global_load_dwordx2 v[72:73], v120, s[6:7]
	s_add_i32 s14, s14, s26
.Lq_ldw:
	s_waitcnt vmcnt(0)
	v_subrev_u32_e32 v120, v202, v207
	v_add_u32_e32 v120, v120, v203
	ds_write_b64 v120, v[40:41]
	s_cmp_le_u32 s12, 1
	s_cbranch_scc1 .Lq_ldd
	ds_write_b64 v120, v[42:43] offset:512
	s_cmp_le_u32 s12, 2
	s_cbranch_scc1 .Lq_ldd
	ds_write_b64 v120, v[44:45] offset:1024
	s_cmp_le_u32 s12, 3
	s_cbranch_scc1 .Lq_ldd
	ds_write_b64 v120, v[46:47] offset:1536
	s_cmp_le_u32 s12, 4
	s_cbranch_scc1 .Lq_ldd
	ds_write_b64 v120, v[48:49] offset:2048
	s_cmp_le_u32 s12, 5
	s_cbranch_scc1 .Lq_ldd
	ds_write_b64 v120, v[50:51] offset:2560
	s_cmp_le_u32 s12, 6
	s_cbranch_scc1 .Lq_ldd
	ds_write_b64 v120, v[52:53] offset:3072
	s_cmp_le_u32 s12, 7
	s_cbranch_scc1 .Lq_ldd
	ds_write_b64 v120, v[54:55] offset:3584
	s_cmp_le_u32 s12, 8
	s_cbranch_scc1 .Lq_ldd
	ds_write_b64 v120, v[56:57] offset:4096
	s_cmp_le_u32 s12, 9
	s_cbranch_scc1 .Lq_ldd
	ds_write_b64 v120, v[58:59] offset:4608
	s_cmp_le_u32 s12, 10
	s_cbranch_scc1 .Lq_ldd
	ds_write_b64 v120, v[60:61] offset:5120
	s_cmp_le_u32 s12, 11
	s_cbranch_scc1 .Lq_ldd
	ds_write_b64 v120, v[62:63] offset:5632
	s_cmp_le_u32 s12, 12
	s_cbranch_scc1 .Lq_ldd
	ds_write_b64 v120, v[64:65] offset:6144
	s_cmp_le_u32 s12, 13
	s_cbranch_scc1 .Lq_ldd
	ds_write_b64 v120, v[66:67] offset:6656
	s_cmp_le_u32 s12, 14
	s_cbranch_scc1 .Lq_ldd
	ds_write_b64 v120, v[68:69] offset:7168
	s_cmp_le_u32 s12, 15
	s_cbranch_scc1 .Lq_ldd
	ds_write_b64 v120, v[70:71] offset:7680
	s_cmp_le_u32 s12, 16
	s_cbranch_scc1 .Lq_ldd
	ds_write_b64 v120, v[72:73] offset:8192
.Lq_ldd:
	s_waitcnt lgkmcnt(0)
	s_mov_b32 s8, 0
.Lq_upass:
	s_mov_b32 s21, s8
	s_lshl_b32 s5, s21, 8
	s_add_u32 s5, s5, 0x8800000
	s_lshl_b32 s4, s21, 7
	s_add_u32 s4, s4, 0x34500000
	v_add_u32_e32 v123, s4, v200
	s_mov_b32 s14, s101
	s_mov_b32 s13, 0
	s_mov_b32 s100, 1
	v_add_u32_e32 v120, s13, v207
	ds_read_b128 v[0:3], v120
	ds_read_b128 v[4:7], v120 offset:16
	ds_read_b128 v[8:11], v120 offset:32
	ds_read_b128 v[12:15], v120 offset:48
	s_lshl_b32 s20, s14, 2
	s_add_u32 s20, s20, s15
	s_waitcnt lgkmcnt(0)
	v_lshl_add_u32 v0, v0, 10, v123
	v_lshl_add_u32 v1, v1, 10, v123
	v_lshl_add_u32 v2, v2, 10, v123
	v_lshl_add_u32 v3, v3, 10, v123
	v_lshl_add_u32 v4, v4, 10, v123
	v_lshl_add_u32 v5, v5, 10, v123
	v_lshl_add_u32 v6, v6, 10, v123
	v_lshl_add_u32 v7, v7, 10, v123
	v_lshl_add_u32 v8, v8, 10, v123
	v_lshl_add_u32 v9, v9, 10, v123
	v_lshl_add_u32 v10, v10, 10, v123
	v_lshl_add_u32 v11, v11, 10, v123
	v_lshl_add_u32 v12, v12, 10, v123
	v_lshl_add_u32 v13, v13, 10, v123
	v_lshl_add_u32 v14, v14, 10, v123
	v_lshl_add_u32 v15, v15, 10, v123
	s_lshl_b32 s1, s20, 11
	s_add_u32 s1, s1, s5
	v_add_u32_e32 v121, s1, v201
	global_load_dwordx4 v[16:19], v121, s[6:7]
	global_load_dwordx4 v[20:23], v121, s[6:7] offset:16
	global_load_dwordx4 v[40:43], v0, s[6:7]
	global_load_dwordx4 v[44:47], v1, s[6:7]
	global_load_dwordx4 v[48:51], v2, s[6:7]
	global_load_dwordx4 v[52:55], v3, s[6:7]
	global_load_dwordx4 v[56:59], v4, s[6:7]
	global_load_dwordx4 v[60:63], v5, s[6:7]
	global_load_dwordx4 v[64:67], v6, s[6:7]
	global_load_dwordx4 v[68:71], v7, s[6:7]
	global_load_dwordx4 v[72:75], v8, s[6:7]
	global_load_dwordx4 v[76:79], v9, s[6:7]
	global_load_dwordx4 v[80:83], v10, s[6:7]
	global_load_dwordx4 v[84:87], v11, s[6:7]
	global_load_dwordx4 v[88:91], v12, s[6:7]
	global_load_dwordx4 v[92:95], v13, s[6:7]
	global_load_dwordx4 v[96:99], v14, s[6:7]
	global_load_dwordx4 v[100:103], v15, s[6:7]
.Lq_utok:
	s_waitcnt vmcnt(16)
	v_lshlrev_b32_e32 v24, 16, v16
	v_and_b32_e32 v25, 0xffff0000, v16
	v_lshlrev_b32_e32 v26, 16, v17
	v_and_b32_e32 v27, 0xffff0000, v17
	v_lshlrev_b32_e32 v28, 16, v18
	v_and_b32_e32 v29, 0xffff0000, v18
	v_lshlrev_b32_e32 v30, 16, v19
	v_and_b32_e32 v31, 0xffff0000, v19
	v_lshlrev_b32_e32 v32, 16, v20
	v_and_b32_e32 v33, 0xffff0000, v20
	v_lshlrev_b32_e32 v34, 16, v21
	v_and_b32_e32 v35, 0xffff0000, v21
	v_lshlrev_b32_e32 v36, 16, v22
	v_and_b32_e32 v37, 0xffff0000, v22
	v_lshlrev_b32_e32 v38, 16, v23
	v_and_b32_e32 v39, 0xffff0000, v23
	v_add_u32_e32 v122, s13, v198
	ds_read_b64 v[124:125], v122
	s_cmp_ge_u32 s100, s12
	s_cbranch_scc1 .Lq_ulast
	s_add_u32 s0, s13, 0x200
	v_add_u32_e32 v120, s0, v207
	ds_read_b128 v[0:3], v120
	ds_read_b128 v[4:7], v120 offset:16
	ds_read_b128 v[8:11], v120 offset:32
	ds_read_b128 v[12:15], v120 offset:48
	s_waitcnt vmcnt(15)
	v_cvt_pk_f32_fp8_e32 v[140:141], v40
	v_cvt_pk_f32_fp8_sdwa v[142:143], v40 src0_sel:WORD_1
	v_mul_f32_e32 v104, v140, v24
	v_fmac_f32_e32 v104, v141, v25
	v_fmac_f32_e32 v104, v142, v26
	v_fmac_f32_e32 v104, v143, v27
	v_cvt_pk_f32_fp8_e32 v[140:141], v41
	v_cvt_pk_f32_fp8_sdwa v[142:143], v41 src0_sel:WORD_1
	v_fmac_f32_e32 v104, v140, v28
	v_fmac_f32_e32 v104, v141, v29
	v_fmac_f32_e32 v104, v142, v30
	v_fmac_f32_e32 v104, v143, v31
	v_cvt_pk_f32_fp8_e32 v[140:141], v42
	v_cvt_pk_f32_fp8_sdwa v[142:143], v42 src0_sel:WORD_1
	v_fmac_f32_e32 v104, v140, v32
	v_fmac_f32_e32 v104, v141, v33
	v_fmac_f32_e32 v104, v142, v34
	v_fmac_f32_e32 v104, v143, v35
	v_cvt_pk_f32_fp8_e32 v[140:141], v43
	v_cvt_pk_f32_fp8_sdwa v[142:143], v43 src0_sel:WORD_1
	v_fmac_f32_e32 v104, v140, v36
	v_fmac_f32_e32 v104, v141, v37
	v_fmac_f32_e32 v104, v142, v38
	v_fmac_f32_e32 v104, v143, v39
	s_waitcnt vmcnt(14)
	v_cvt_pk_f32_fp8_e32 v[140:141], v44
	v_cvt_pk_f32_fp8_sdwa v[142:143], v44 src0_sel:WORD_1
	v_mul_f32_e32 v105, v140, v24
	v_fmac_f32_e32 v105, v141, v25
	v_fmac_f32_e32 v105, v142, v26
	v_fmac_f32_e32 v105, v143, v27
	v_cvt_pk_f32_fp8_e32 v[140:141], v45
	v_cvt_pk_f32_fp8_sdwa v[142:143], v45 src0_sel:WORD_1
	v_fmac_f32_e32 v105, v140, v28
	v_fmac_f32_e32 v105, v141, v29
	v_fmac_f32_e32 v105, v142, v30
	v_fmac_f32_e32 v105, v143, v31
	v_cvt_pk_f32_fp8_e32 v[140:141], v46
	v_cvt_pk_f32_fp8_sdwa v[142:143], v46 src0_sel:WORD_1
	v_fmac_f32_e32 v105, v140, v32
	v_fmac_f32_e32 v105, v141, v33
	v_fmac_f32_e32 v105, v142, v34
	v_fmac_f32_e32 v105, v143, v35
	v_cvt_pk_f32_fp8_e32 v[140:141], v47
	v_cvt_pk_f32_fp8_sdwa v[142:143], v47 src0_sel:WORD_1
	v_fmac_f32_e32 v105, v140, v36
	v_fmac_f32_e32 v105, v141, v37
	v_fmac_f32_e32 v105, v142, v38
	v_fmac_f32_e32 v105, v143, v39
	s_waitcnt vmcnt(13)
	v_cvt_pk_f32_fp8_e32 v[140:141], v48
	v_cvt_pk_f32_fp8_sdwa v[142:143], v48 src0_sel:WORD_1
	v_mul_f32_e32 v106, v140, v24
	v_fmac_f32_e32 v106, v141, v25
	v_fmac_f32_e32 v106, v142, v26
	v_fmac_f32_e32 v106, v143, v27
	v_cvt_pk_f32_fp8_e32 v[140:141], v49
	v_cvt_pk_f32_fp8_sdwa v[142:143], v49 src0_sel:WORD_1
	v_fmac_f32_e32 v106, v140, v28
	v_fmac_f32_e32 v106, v141, v29
	v_fmac_f32_e32 v106, v142, v30
	v_fmac_f32_e32 v106, v143, v31
	v_cvt_pk_f32_fp8_e32 v[140:141], v50
	v_cvt_pk_f32_fp8_sdwa v[142:143], v50 src0_sel:WORD_1
	v_fmac_f32_e32 v106, v140, v32
	v_fmac_f32_e32 v106, v141, v33
	v_fmac_f32_e32 v106, v142, v34
	v_fmac_f32_e32 v106, v143, v35
	v_cvt_pk_f32_fp8_e32 v[140:141], v51
	v_cvt_pk_f32_fp8_sdwa v[142:143], v51 src0_sel:WORD_1
	v_fmac_f32_e32 v106, v140, v36
	v_fmac_f32_e32 v106, v141, v37
	v_fmac_f32_e32 v106, v142, v38
	v_fmac_f32_e32 v106, v143, v39
	s_waitcnt vmcnt(12)
	v_cvt_pk_f32_fp8_e32 v[140:141], v52
	v_cvt_pk_f32_fp8_sdwa v[142:143], v52 src0_sel:WORD_1
	v_mul_f32_e32 v107, v140, v24
	v_fmac_f32_e32 v107, v141, v25
	v_fmac_f32_e32 v107, v142, v26
	v_fmac_f32_e32 v107, v143, v27
	v_cvt_pk_f32_fp8_e32 v[140:141], v53
	v_cvt_pk_f32_fp8_sdwa v[142:143], v53 src0_sel:WORD_1
	v_fmac_f32_e32 v107, v140, v28
	v_fmac_f32_e32 v107, v141, v29
	v_fmac_f32_e32 v107, v142, v30
	v_fmac_f32_e32 v107, v143, v31
	v_cvt_pk_f32_fp8_e32 v[140:141], v54
	v_cvt_pk_f32_fp8_sdwa v[142:143], v54 src0_sel:WORD_1
	v_fmac_f32_e32 v107, v140, v32
	v_fmac_f32_e32 v107, v141, v33
	v_fmac_f32_e32 v107, v142, v34
	v_fmac_f32_e32 v107, v143, v35
	v_cvt_pk_f32_fp8_e32 v[140:141], v55
	v_cvt_pk_f32_fp8_sdwa v[142:143], v55 src0_sel:WORD_1
	v_fmac_f32_e32 v107, v140, v36
	v_fmac_f32_e32 v107, v141, v37
	v_fmac_f32_e32 v107, v142, v38
	v_fmac_f32_e32 v107, v143, v39
	s_waitcnt vmcnt(11)
	v_cvt_pk_f32_fp8_e32 v[140:141], v56
	v_cvt_pk_f32_fp8_sdwa v[142:143], v56 src0_sel:WORD_1
	v_mul_f32_e32 v108, v140, v24
	v_fmac_f32_e32 v108, v141, v25
	v_fmac_f32_e32 v108, v142, v26
	v_fmac_f32_e32 v108, v143, v27
	v_cvt_pk_f32_fp8_e32 v[140:141], v57
	v_cvt_pk_f32_fp8_sdwa v[142:143], v57 src0_sel:WORD_1
	v_fmac_f32_e32 v108, v140, v28
	v_fmac_f32_e32 v108, v141, v29
	v_fmac_f32_e32 v108, v142, v30
	v_fmac_f32_e32 v108, v143, v31
	v_cvt_pk_f32_fp8_e32 v[140:141], v58
	v_cvt_pk_f32_fp8_sdwa v[142:143], v58 src0_sel:WORD_1
	v_fmac_f32_e32 v108, v140, v32
	v_fmac_f32_e32 v108, v141, v33
	v_fmac_f32_e32 v108, v142, v34
	v_fmac_f32_e32 v108, v143, v35
	v_cvt_pk_f32_fp8_e32 v[140:141], v59
	v_cvt_pk_f32_fp8_sdwa v[142:143], v59 src0_sel:WORD_1
	v_fmac_f32_e32 v108, v140, v36
	v_fmac_f32_e32 v108, v141, v37
	v_fmac_f32_e32 v108, v142, v38
	v_fmac_f32_e32 v108, v143, v39
	s_waitcnt vmcnt(10)
	v_cvt_pk_f32_fp8_e32 v[140:141], v60
	v_cvt_pk_f32_fp8_sdwa v[142:143], v60 src0_sel:WORD_1
	v_mul_f32_e32 v109, v140, v24
	v_fmac_f32_e32 v109, v141, v25
	v_fmac_f32_e32 v109, v142, v26
	v_fmac_f32_e32 v109, v143, v27
	v_cvt_pk_f32_fp8_e32 v[140:141], v61
	v_cvt_pk_f32_fp8_sdwa v[142:143], v61 src0_sel:WORD_1
	v_fmac_f32_e32 v109, v140, v28
	v_fmac_f32_e32 v109, v141, v29
	v_fmac_f32_e32 v109, v142, v30
	v_fmac_f32_e32 v109, v143, v31
	v_cvt_pk_f32_fp8_e32 v[140:141], v62
	v_cvt_pk_f32_fp8_sdwa v[142:143], v62 src0_sel:WORD_1
	v_fmac_f32_e32 v109, v140, v32
	v_fmac_f32_e32 v109, v141, v33
	v_fmac_f32_e32 v109, v142, v34
	v_fmac_f32_e32 v109, v143, v35
	v_cvt_pk_f32_fp8_e32 v[140:141], v63
	v_cvt_pk_f32_fp8_sdwa v[142:143], v63 src0_sel:WORD_1
	v_fmac_f32_e32 v109, v140, v36
	v_fmac_f32_e32 v109, v141, v37
	v_fmac_f32_e32 v109, v142, v38
	v_fmac_f32_e32 v109, v143, v39
	s_waitcnt vmcnt(9)
	v_cvt_pk_f32_fp8_e32 v[140:141], v64
	v_cvt_pk_f32_fp8_sdwa v[142:143], v64 src0_sel:WORD_1
	v_mul_f32_e32 v110, v140, v24
	v_fmac_f32_e32 v110, v141, v25
	v_fmac_f32_e32 v110, v142, v26
	v_fmac_f32_e32 v110, v143, v27
	v_cvt_pk_f32_fp8_e32 v[140:141], v65
	v_cvt_pk_f32_fp8_sdwa v[142:143], v65 src0_sel:WORD_1
	v_fmac_f32_e32 v110, v140, v28
	v_fmac_f32_e32 v110, v141, v29
	v_fmac_f32_e32 v110, v142, v30
	v_fmac_f32_e32 v110, v143, v31
	v_cvt_pk_f32_fp8_e32 v[140:141], v66
	v_cvt_pk_f32_fp8_sdwa v[142:143], v66 src0_sel:WORD_1
	v_fmac_f32_e32 v110, v140, v32
	v_fmac_f32_e32 v110, v141, v33
	v_fmac_f32_e32 v110, v142, v34
	v_fmac_f32_e32 v110, v143, v35
	v_cvt_pk_f32_fp8_e32 v[140:141], v67
	v_cvt_pk_f32_fp8_sdwa v[142:143], v67 src0_sel:WORD_1
	v_fmac_f32_e32 v110, v140, v36
	v_fmac_f32_e32 v110, v141, v37
	v_fmac_f32_e32 v110, v142, v38
	v_fmac_f32_e32 v110, v143, v39
	s_waitcnt vmcnt(8)
	v_cvt_pk_f32_fp8_e32 v[140:141], v68
	v_cvt_pk_f32_fp8_sdwa v[142:143], v68 src0_sel:WORD_1
	v_mul_f32_e32 v111, v140, v24
	v_fmac_f32_e32 v111, v141, v25
	v_fmac_f32_e32 v111, v142, v26
	v_fmac_f32_e32 v111, v143, v27
	v_cvt_pk_f32_fp8_e32 v[140:141], v69
	v_cvt_pk_f32_fp8_sdwa v[142:143], v69 src0_sel:WORD_1
	v_fmac_f32_e32 v111, v140, v28
	v_fmac_f32_e32 v111, v141, v29
	v_fmac_f32_e32 v111, v142, v30
	v_fmac_f32_e32 v111, v143, v31
	v_cvt_pk_f32_fp8_e32 v[140:141], v70
	v_cvt_pk_f32_fp8_sdwa v[142:143], v70 src0_sel:WORD_1
	v_fmac_f32_e32 v111, v140, v32
	v_fmac_f32_e32 v111, v141, v33
	v_fmac_f32_e32 v111, v142, v34
	v_fmac_f32_e32 v111, v143, v35
	v_cvt_pk_f32_fp8_e32 v[140:141], v71
	v_cvt_pk_f32_fp8_sdwa v[142:143], v71 src0_sel:WORD_1
	v_fmac_f32_e32 v111, v140, v36
	v_fmac_f32_e32 v111, v141, v37
	v_fmac_f32_e32 v111, v142, v38
	v_fmac_f32_e32 v111, v143, v39
	s_add_i32 s0, s14, s26
	s_lshl_b32 s1, s0, 2
	s_add_u32 s1, s1, s15
	s_mov_b32 s20, s1
	s_waitcnt lgkmcnt(0)
	v_lshl_add_u32 v0, v0, 10, v123
	v_lshl_add_u32 v1, v1, 10, v123
	v_lshl_add_u32 v2, v2, 10, v123
	v_lshl_add_u32 v3, v3, 10, v123
	v_lshl_add_u32 v4, v4, 10, v123
	v_lshl_add_u32 v5, v5, 10, v123
	v_lshl_add_u32 v6, v6, 10, v123
	v_lshl_add_u32 v7, v7, 10, v123
	v_lshl_add_u32 v8, v8, 10, v123
	v_lshl_add_u32 v9, v9, 10, v123
	v_lshl_add_u32 v10, v10, 10, v123
	v_lshl_add_u32 v11, v11, 10, v123
	v_lshl_add_u32 v12, v12, 10, v123
	v_lshl_add_u32 v13, v13, 10, v123
	v_lshl_add_u32 v14, v14, 10, v123
	v_lshl_add_u32 v15, v15, 10, v123
	s_lshl_b32 s1, s20, 11
	s_add_u32 s1, s1, s5
	v_add_u32_e32 v121, s1, v201
	global_load_dwordx4 v[16:19], v121, s[6:7]
	global_load_dwordx4 v[20:23], v121, s[6:7] offset:16
	global_load_dwordx4 v[40:43], v0, s[6:7]
	global_load_dwordx4 v[44:47], v1, s[6:7]
	global_load_dwordx4 v[48:51], v2, s[6:7]
	global_load_dwordx4 v[52:55], v3, s[6:7]
	global_load_dwordx4 v[56:59], v4, s[6:7]
	global_load_dwordx4 v[60:63], v5, s[6:7]
	global_load_dwordx4 v[64:67], v6, s[6:7]
	global_load_dwordx4 v[68:71], v7, s[6:7]
	s_waitcnt vmcnt(17)
	v_cvt_pk_f32_fp8_e32 v[140:141], v72
	v_cvt_pk_f32_fp8_sdwa v[142:143], v72 src0_sel:WORD_1
	v_mul_f32_e32 v112, v140, v24
	v_fmac_f32_e32 v112, v141, v25
	v_fmac_f32_e32 v112, v142, v26
	v_fmac_f32_e32 v112, v143, v27
	v_cvt_pk_f32_fp8_e32 v[140:141], v73
	v_cvt_pk_f32_fp8_sdwa v[142:143], v73 src0_sel:WORD_1
	v_fmac_f32_e32 v112, v140, v28
	v_fmac_f32_e32 v112, v141, v29
	v_fmac_f32_e32 v112, v142, v30
	v_fmac_f32_e32 v112, v143, v31
	v_cvt_pk_f32_fp8_e32 v[140:141], v74
	v_cvt_pk_f32_fp8_sdwa v[142:143], v74 src0_sel:WORD_1
	v_fmac_f32_e32 v112, v140, v32
	v_fmac_f32_e32 v112, v141, v33
	v_fmac_f32_e32 v112, v142, v34
	v_fmac_f32_e32 v112, v143, v35
	v_cvt_pk_f32_fp8_e32 v[140:141], v75
	v_cvt_pk_f32_fp8_sdwa v[142:143], v75 src0_sel:WORD_1
	v_fmac_f32_e32 v112, v140, v36
	v_fmac_f32_e32 v112, v141, v37
	v_fmac_f32_e32 v112, v142, v38
	v_fmac_f32_e32 v112, v143, v39
	s_waitcnt vmcnt(16)
	v_cvt_pk_f32_fp8_e32 v[140:141], v76
	v_cvt_pk_f32_fp8_sdwa v[142:143], v76 src0_sel:WORD_1
	v_mul_f32_e32 v113, v140, v24
	v_fmac_f32_e32 v113, v141, v25
	v_fmac_f32_e32 v113, v142, v26
	v_fmac_f32_e32 v113, v143, v27
	v_cvt_pk_f32_fp8_e32 v[140:141], v77
	v_cvt_pk_f32_fp8_sdwa v[142:143], v77 src0_sel:WORD_1
	v_fmac_f32_e32 v113, v140, v28
	v_fmac_f32_e32 v113, v141, v29
	v_fmac_f32_e32 v113, v142, v30
	v_fmac_f32_e32 v113, v143, v31
	v_cvt_pk_f32_fp8_e32 v[140:141], v78
	v_cvt_pk_f32_fp8_sdwa v[142:143], v78 src0_sel:WORD_1
	v_fmac_f32_e32 v113, v140, v32
	v_fmac_f32_e32 v113, v141, v33
	v_fmac_f32_e32 v113, v142, v34
	v_fmac_f32_e32 v113, v143, v35
	v_cvt_pk_f32_fp8_e32 v[140:141], v79
	v_cvt_pk_f32_fp8_sdwa v[142:143], v79 src0_sel:WORD_1
	v_fmac_f32_e32 v113, v140, v36
	v_fmac_f32_e32 v113, v141, v37
	v_fmac_f32_e32 v113, v142, v38
	v_fmac_f32_e32 v113, v143, v39
	s_waitcnt vmcnt(15)
	v_cvt_pk_f32_fp8_e32 v[140:141], v80
	v_cvt_pk_f32_fp8_sdwa v[142:143], v80 src0_sel:WORD_1
	v_mul_f32_e32 v114, v140, v24
	v_fmac_f32_e32 v114, v141, v25
	v_fmac_f32_e32 v114, v142, v26
	v_fmac_f32_e32 v114, v143, v27
	v_cvt_pk_f32_fp8_e32 v[140:141], v81
	v_cvt_pk_f32_fp8_sdwa v[142:143], v81 src0_sel:WORD_1
	v_fmac_f32_e32 v114, v140, v28
	v_fmac_f32_e32 v114, v141, v29
	v_fmac_f32_e32 v114, v142, v30
	v_fmac_f32_e32 v114, v143, v31
	v_cvt_pk_f32_fp8_e32 v[140:141], v82
	v_cvt_pk_f32_fp8_sdwa v[142:143], v82 src0_sel:WORD_1
	v_fmac_f32_e32 v114, v140, v32
	v_fmac_f32_e32 v114, v141, v33
	v_fmac_f32_e32 v114, v142, v34
	v_fmac_f32_e32 v114, v143, v35
	v_cvt_pk_f32_fp8_e32 v[140:141], v83
	v_cvt_pk_f32_fp8_sdwa v[142:143], v83 src0_sel:WORD_1
	v_fmac_f32_e32 v114, v140, v36
	v_fmac_f32_e32 v114, v141, v37
	v_fmac_f32_e32 v114, v142, v38
	v_fmac_f32_e32 v114, v143, v39
	s_waitcnt vmcnt(14)
	v_cvt_pk_f32_fp8_e32 v[140:141], v84
	v_cvt_pk_f32_fp8_sdwa v[142:143], v84 src0_sel:WORD_1
	v_mul_f32_e32 v115, v140, v24
	v_fmac_f32_e32 v115, v141, v25
	v_fmac_f32_e32 v115, v142, v26
	v_fmac_f32_e32 v115, v143, v27
	v_cvt_pk_f32_fp8_e32 v[140:141], v85
	v_cvt_pk_f32_fp8_sdwa v[142:143], v85 src0_sel:WORD_1
	v_fmac_f32_e32 v115, v140, v28
	v_fmac_f32_e32 v115, v141, v29
	v_fmac_f32_e32 v115, v142, v30
	v_fmac_f32_e32 v115, v143, v31
	v_cvt_pk_f32_fp8_e32 v[140:141], v86
	v_cvt_pk_f32_fp8_sdwa v[142:143], v86 src0_sel:WORD_1
	v_fmac_f32_e32 v115, v140, v32
	v_fmac_f32_e32 v115, v141, v33
	v_fmac_f32_e32 v115, v142, v34
	v_fmac_f32_e32 v115, v143, v35
	v_cvt_pk_f32_fp8_e32 v[140:141], v87
	v_cvt_pk_f32_fp8_sdwa v[142:143], v87 src0_sel:WORD_1
	v_fmac_f32_e32 v115, v140, v36
	v_fmac_f32_e32 v115, v141, v37
	v_fmac_f32_e32 v115, v142, v38
	v_fmac_f32_e32 v115, v143, v39
	s_waitcnt vmcnt(13)
	v_cvt_pk_f32_fp8_e32 v[140:141], v88
	v_cvt_pk_f32_fp8_sdwa v[142:143], v88 src0_sel:WORD_1
	v_mul_f32_e32 v116, v140, v24
	v_fmac_f32_e32 v116, v141, v25
	v_fmac_f32_e32 v116, v142, v26
	v_fmac_f32_e32 v116, v143, v27
	v_cvt_pk_f32_fp8_e32 v[140:141], v89
	v_cvt_pk_f32_fp8_sdwa v[142:143], v89 src0_sel:WORD_1
	v_fmac_f32_e32 v116, v140, v28
	v_fmac_f32_e32 v116, v141, v29
	v_fmac_f32_e32 v116, v142, v30
	v_fmac_f32_e32 v116, v143, v31
	v_cvt_pk_f32_fp8_e32 v[140:141], v90
	v_cvt_pk_f32_fp8_sdwa v[142:143], v90 src0_sel:WORD_1
	v_fmac_f32_e32 v116, v140, v32
	v_fmac_f32_e32 v116, v141, v33
	v_fmac_f32_e32 v116, v142, v34
	v_fmac_f32_e32 v116, v143, v35
	v_cvt_pk_f32_fp8_e32 v[140:141], v91
	v_cvt_pk_f32_fp8_sdwa v[142:143], v91 src0_sel:WORD_1
	v_fmac_f32_e32 v116, v140, v36
	v_fmac_f32_e32 v116, v141, v37
	v_fmac_f32_e32 v116, v142, v38
	v_fmac_f32_e32 v116, v143, v39
	s_waitcnt vmcnt(12)
	v_cvt_pk_f32_fp8_e32 v[140:141], v92
	v_cvt_pk_f32_fp8_sdwa v[142:143], v92 src0_sel:WORD_1
	v_mul_f32_e32 v117, v140, v24
	v_fmac_f32_e32 v117, v141, v25
	v_fmac_f32_e32 v117, v142, v26
	v_fmac_f32_e32 v117, v143, v27
	v_cvt_pk_f32_fp8_e32 v[140:141], v93
	v_cvt_pk_f32_fp8_sdwa v[142:143], v93 src0_sel:WORD_1
	v_fmac_f32_e32 v117, v140, v28
	v_fmac_f32_e32 v117, v141, v29
	v_fmac_f32_e32 v117, v142, v30
	v_fmac_f32_e32 v117, v143, v31
	v_cvt_pk_f32_fp8_e32 v[140:141], v94
	v_cvt_pk_f32_fp8_sdwa v[142:143], v94 src0_sel:WORD_1
	v_fmac_f32_e32 v117, v140, v32
	v_fmac_f32_e32 v117, v141, v33
	v_fmac_f32_e32 v117, v142, v34
	v_fmac_f32_e32 v117, v143, v35
	v_cvt_pk_f32_fp8_e32 v[140:141], v95
	v_cvt_pk_f32_fp8_sdwa v[142:143], v95 src0_sel:WORD_1
	v_fmac_f32_e32 v117, v140, v36
	v_fmac_f32_e32 v117, v141, v37
	v_fmac_f32_e32 v117, v142, v38
	v_fmac_f32_e32 v117, v143, v39
	s_waitcnt vmcnt(11)
	v_cvt_pk_f32_fp8_e32 v[140:141], v96
	v_cvt_pk_f32_fp8_sdwa v[142:143], v96 src0_sel:WORD_1
	v_mul_f32_e32 v118, v140, v24
	v_fmac_f32_e32 v118, v141, v25
	v_fmac_f32_e32 v118, v142, v26
	v_fmac_f32_e32 v118, v143, v27
	v_cvt_pk_f32_fp8_e32 v[140:141], v97
	v_cvt_pk_f32_fp8_sdwa v[142:143], v97 src0_sel:WORD_1
	v_fmac_f32_e32 v118, v140, v28
	v_fmac_f32_e32 v118, v141, v29
	v_fmac_f32_e32 v118, v142, v30
	v_fmac_f32_e32 v118, v143, v31
	v_cvt_pk_f32_fp8_e32 v[140:141], v98
	v_cvt_pk_f32_fp8_sdwa v[142:143], v98 src0_sel:WORD_1
	v_fmac_f32_e32 v118, v140, v32
	v_fmac_f32_e32 v118, v141, v33
	v_fmac_f32_e32 v118, v142, v34
	v_fmac_f32_e32 v118, v143, v35
	v_cvt_pk_f32_fp8_e32 v[140:141], v99
	v_cvt_pk_f32_fp8_sdwa v[142:143], v99 src0_sel:WORD_1
	v_fmac_f32_e32 v118, v140, v36
	v_fmac_f32_e32 v118, v141, v37
	v_fmac_f32_e32 v118, v142, v38
	v_fmac_f32_e32 v118, v143, v39
	s_waitcnt vmcnt(10)
	v_cvt_pk_f32_fp8_e32 v[140:141], v100
	v_cvt_pk_f32_fp8_sdwa v[142:143], v100 src0_sel:WORD_1
	v_mul_f32_e32 v119, v140, v24
	v_fmac_f32_e32 v119, v141, v25
	v_fmac_f32_e32 v119, v142, v26
	v_fmac_f32_e32 v119, v143, v27
	v_cvt_pk_f32_fp8_e32 v[140:141], v101
	v_cvt_pk_f32_fp8_sdwa v[142:143], v101 src0_sel:WORD_1
	v_fmac_f32_e32 v119, v140, v28
	v_fmac_f32_e32 v119, v141, v29
	v_fmac_f32_e32 v119, v142, v30
	v_fmac_f32_e32 v119, v143, v31
	v_cvt_pk_f32_fp8_e32 v[140:141], v102
	v_cvt_pk_f32_fp8_sdwa v[142:143], v102 src0_sel:WORD_1
	v_fmac_f32_e32 v119, v140, v32
	v_fmac_f32_e32 v119, v141, v33
	v_fmac_f32_e32 v119, v142, v34
	v_fmac_f32_e32 v119, v143, v35
	v_cvt_pk_f32_fp8_e32 v[140:141], v103
	v_cvt_pk_f32_fp8_sdwa v[142:143], v103 src0_sel:WORD_1
	v_fmac_f32_e32 v119, v140, v36
	v_fmac_f32_e32 v119, v141, v37
	v_fmac_f32_e32 v119, v142, v38
	v_fmac_f32_e32 v119, v143, v39
	global_load_dwordx4 v[72:75], v8, s[6:7]
	global_load_dwordx4 v[76:79], v9, s[6:7]
	global_load_dwordx4 v[80:83], v10, s[6:7]
	global_load_dwordx4 v[84:87], v11, s[6:7]
	global_load_dwordx4 v[88:91], v12, s[6:7]
	global_load_dwordx4 v[92:95], v13, s[6:7]
	global_load_dwordx4 v[96:99], v14, s[6:7]
	global_load_dwordx4 v[100:103], v15, s[6:7]
	s_branch .Lq_ured
.Lq_ulast:
	s_waitcnt vmcnt(15)
	v_cvt_pk_f32_fp8_e32 v[140:141], v40
	v_cvt_pk_f32_fp8_sdwa v[142:143], v40 src0_sel:WORD_1
	v_mul_f32_e32 v104, v140, v24
	v_fmac_f32_e32 v104, v141, v25
	v_fmac_f32_e32 v104, v142, v26
	v_fmac_f32_e32 v104, v143, v27
	v_cvt_pk_f32_fp8_e32 v[140:141], v41
	v_cvt_pk_f32_fp8_sdwa v[142:143], v41 src0_sel:WORD_1
	v_fmac_f32_e32 v104, v140, v28
	v_fmac_f32_e32 v104, v141, v29
	v_fmac_f32_e32 v104, v142, v30
	v_fmac_f32_e32 v104, v143, v31
	v_cvt_pk_f32_fp8_e32 v[140:141], v42
	v_cvt_pk_f32_fp8_sdwa v[142:143], v42 src0_sel:WORD_1
	v_fmac_f32_e32 v104, v140, v32
	v_fmac_f32_e32 v104, v141, v33
	v_fmac_f32_e32 v104, v142, v34
	v_fmac_f32_e32 v104, v143, v35
	v_cvt_pk_f32_fp8_e32 v[140:141], v43
	v_cvt_pk_f32_fp8_sdwa v[142:143], v43 src0_sel:WORD_1
	v_fmac_f32_e32 v104, v140, v36
	v_fmac_f32_e32 v104, v141, v37
	v_fmac_f32_e32 v104, v142, v38
	v_fmac_f32_e32 v104, v143, v39
	s_waitcnt vmcnt(14)
	v_cvt_pk_f32_fp8_e32 v[140:141], v44
	v_cvt_pk_f32_fp8_sdwa v[142:143], v44 src0_sel:WORD_1
	v_mul_f32_e32 v105, v140, v24
	v_fmac_f32_e32 v105, v141, v25
	v_fmac_f32_e32 v105, v142, v26
	v_fmac_f32_e32 v105, v143, v27
	v_cvt_pk_f32_fp8_e32 v[140:141], v45
	v_cvt_pk_f32_fp8_sdwa v[142:143], v45 src0_sel:WORD_1
	v_fmac_f32_e32 v105, v140, v28
	v_fmac_f32_e32 v105, v141, v29
	v_fmac_f32_e32 v105, v142, v30
	v_fmac_f32_e32 v105, v143, v31
	v_cvt_pk_f32_fp8_e32 v[140:141], v46
	v_cvt_pk_f32_fp8_sdwa v[142:143], v46 src0_sel:WORD_1
	v_fmac_f32_e32 v105, v140, v32
	v_fmac_f32_e32 v105, v141, v33
	v_fmac_f32_e32 v105, v142, v34
	v_fmac_f32_e32 v105, v143, v35
	v_cvt_pk_f32_fp8_e32 v[140:141], v47
	v_cvt_pk_f32_fp8_sdwa v[142:143], v47 src0_sel:WORD_1
	v_fmac_f32_e32 v105, v140, v36
	v_fmac_f32_e32 v105, v141, v37
	v_fmac_f32_e32 v105, v142, v38
	v_fmac_f32_e32 v105, v143, v39
	s_waitcnt vmcnt(13)
	v_cvt_pk_f32_fp8_e32 v[140:141], v48
	v_cvt_pk_f32_fp8_sdwa v[142:143], v48 src0_sel:WORD_1
	v_mul_f32_e32 v106, v140, v24
	v_fmac_f32_e32 v106, v141, v25
	v_fmac_f32_e32 v106, v142, v26
	v_fmac_f32_e32 v106, v143, v27
	v_cvt_pk_f32_fp8_e32 v[140:141], v49
	v_cvt_pk_f32_fp8_sdwa v[142:143], v49 src0_sel:WORD_1
	v_fmac_f32_e32 v106, v140, v28
	v_fmac_f32_e32 v106, v141, v29
	v_fmac_f32_e32 v106, v142, v30
	v_fmac_f32_e32 v106, v143, v31
	v_cvt_pk_f32_fp8_e32 v[140:141], v50
	v_cvt_pk_f32_fp8_sdwa v[142:143], v50 src0_sel:WORD_1
	v_fmac_f32_e32 v106, v140, v32
	v_fmac_f32_e32 v106, v141, v33
	v_fmac_f32_e32 v106, v142, v34
	v_fmac_f32_e32 v106, v143, v35
	v_cvt_pk_f32_fp8_e32 v[140:141], v51
	v_cvt_pk_f32_fp8_sdwa v[142:143], v51 src0_sel:WORD_1
	v_fmac_f32_e32 v106, v140, v36
	v_fmac_f32_e32 v106, v141, v37
	v_fmac_f32_e32 v106, v142, v38
	v_fmac_f32_e32 v106, v143, v39
	s_waitcnt vmcnt(12)
	v_cvt_pk_f32_fp8_e32 v[140:141], v52
	v_cvt_pk_f32_fp8_sdwa v[142:143], v52 src0_sel:WORD_1
	v_mul_f32_e32 v107, v140, v24
	v_fmac_f32_e32 v107, v141, v25
	v_fmac_f32_e32 v107, v142, v26
	v_fmac_f32_e32 v107, v143, v27
	v_cvt_pk_f32_fp8_e32 v[140:141], v53
	v_cvt_pk_f32_fp8_sdwa v[142:143], v53 src0_sel:WORD_1
	v_fmac_f32_e32 v107, v140, v28
	v_fmac_f32_e32 v107, v141, v29
	v_fmac_f32_e32 v107, v142, v30
	v_fmac_f32_e32 v107, v143, v31
	v_cvt_pk_f32_fp8_e32 v[140:141], v54
	v_cvt_pk_f32_fp8_sdwa v[142:143], v54 src0_sel:WORD_1
	v_fmac_f32_e32 v107, v140, v32
	v_fmac_f32_e32 v107, v141, v33
	v_fmac_f32_e32 v107, v142, v34
	v_fmac_f32_e32 v107, v143, v35
	v_cvt_pk_f32_fp8_e32 v[140:141], v55
	v_cvt_pk_f32_fp8_sdwa v[142:143], v55 src0_sel:WORD_1
	v_fmac_f32_e32 v107, v140, v36
	v_fmac_f32_e32 v107, v141, v37
	v_fmac_f32_e32 v107, v142, v38
	v_fmac_f32_e32 v107, v143, v39
	s_waitcnt vmcnt(11)
	v_cvt_pk_f32_fp8_e32 v[140:141], v56
	v_cvt_pk_f32_fp8_sdwa v[142:143], v56 src0_sel:WORD_1
	v_mul_f32_e32 v108, v140, v24
	v_fmac_f32_e32 v108, v141, v25
	v_fmac_f32_e32 v108, v142, v26
	v_fmac_f32_e32 v108, v143, v27
	v_cvt_pk_f32_fp8_e32 v[140:141], v57
	v_cvt_pk_f32_fp8_sdwa v[142:143], v57 src0_sel:WORD_1
	v_fmac_f32_e32 v108, v140, v28
	v_fmac_f32_e32 v108, v141, v29
	v_fmac_f32_e32 v108, v142, v30
	v_fmac_f32_e32 v108, v143, v31
	v_cvt_pk_f32_fp8_e32 v[140:141], v58
	v_cvt_pk_f32_fp8_sdwa v[142:143], v58 src0_sel:WORD_1
	v_fmac_f32_e32 v108, v140, v32
	v_fmac_f32_e32 v108, v141, v33
	v_fmac_f32_e32 v108, v142, v34
	v_fmac_f32_e32 v108, v143, v35
	v_cvt_pk_f32_fp8_e32 v[140:141], v59
	v_cvt_pk_f32_fp8_sdwa v[142:143], v59 src0_sel:WORD_1
	v_fmac_f32_e32 v108, v140, v36
	v_fmac_f32_e32 v108, v141, v37
	v_fmac_f32_e32 v108, v142, v38
	v_fmac_f32_e32 v108, v143, v39
	s_waitcnt vmcnt(10)
	v_cvt_pk_f32_fp8_e32 v[140:141], v60
	v_cvt_pk_f32_fp8_sdwa v[142:143], v60 src0_sel:WORD_1
	v_mul_f32_e32 v109, v140, v24
	v_fmac_f32_e32 v109, v141, v25
	v_fmac_f32_e32 v109, v142, v26
	v_fmac_f32_e32 v109, v143, v27
	v_cvt_pk_f32_fp8_e32 v[140:141], v61
	v_cvt_pk_f32_fp8_sdwa v[142:143], v61 src0_sel:WORD_1
	v_fmac_f32_e32 v109, v140, v28
	v_fmac_f32_e32 v109, v141, v29
	v_fmac_f32_e32 v109, v142, v30
	v_fmac_f32_e32 v109, v143, v31
	v_cvt_pk_f32_fp8_e32 v[140:141], v62
	v_cvt_pk_f32_fp8_sdwa v[142:143], v62 src0_sel:WORD_1
	v_fmac_f32_e32 v109, v140, v32
	v_fmac_f32_e32 v109, v141, v33
	v_fmac_f32_e32 v109, v142, v34
	v_fmac_f32_e32 v109, v143, v35
	v_cvt_pk_f32_fp8_e32 v[140:141], v63
	v_cvt_pk_f32_fp8_sdwa v[142:143], v63 src0_sel:WORD_1
	v_fmac_f32_e32 v109, v140, v36
	v_fmac_f32_e32 v109, v141, v37
	v_fmac_f32_e32 v109, v142, v38
	v_fmac_f32_e32 v109, v143, v39
	s_waitcnt vmcnt(9)
	v_cvt_pk_f32_fp8_e32 v[140:141], v64
	v_cvt_pk_f32_fp8_sdwa v[142:143], v64 src0_sel:WORD_1
	v_mul_f32_e32 v110, v140, v24
	v_fmac_f32_e32 v110, v141, v25
	v_fmac_f32_e32 v110, v142, v26
	v_fmac_f32_e32 v110, v143, v27
	v_cvt_pk_f32_fp8_e32 v[140:141], v65
	v_cvt_pk_f32_fp8_sdwa v[142:143], v65 src0_sel:WORD_1
	v_fmac_f32_e32 v110, v140, v28
	v_fmac_f32_e32 v110, v141, v29
	v_fmac_f32_e32 v110, v142, v30
	v_fmac_f32_e32 v110, v143, v31
	v_cvt_pk_f32_fp8_e32 v[140:141], v66
	v_cvt_pk_f32_fp8_sdwa v[142:143], v66 src0_sel:WORD_1
	v_fmac_f32_e32 v110, v140, v32
	v_fmac_f32_e32 v110, v141, v33
	v_fmac_f32_e32 v110, v142, v34
	v_fmac_f32_e32 v110, v143, v35
	v_cvt_pk_f32_fp8_e32 v[140:141], v67
	v_cvt_pk_f32_fp8_sdwa v[142:143], v67 src0_sel:WORD_1
	v_fmac_f32_e32 v110, v140, v36
	v_fmac_f32_e32 v110, v141, v37
	v_fmac_f32_e32 v110, v142, v38
	v_fmac_f32_e32 v110, v143, v39
	s_waitcnt vmcnt(8)
	v_cvt_pk_f32_fp8_e32 v[140:141], v68
	v_cvt_pk_f32_fp8_sdwa v[142:143], v68 src0_sel:WORD_1
	v_mul_f32_e32 v111, v140, v24
	v_fmac_f32_e32 v111, v141, v25
	v_fmac_f32_e32 v111, v142, v26
	v_fmac_f32_e32 v111, v143, v27
	v_cvt_pk_f32_fp8_e32 v[140:141], v69
	v_cvt_pk_f32_fp8_sdwa v[142:143], v69 src0_sel:WORD_1
	v_fmac_f32_e32 v111, v140, v28
	v_fmac_f32_e32 v111, v141, v29
	v_fmac_f32_e32 v111, v142, v30
	v_fmac_f32_e32 v111, v143, v31
	v_cvt_pk_f32_fp8_e32 v[140:141], v70
	v_cvt_pk_f32_fp8_sdwa v[142:143], v70 src0_sel:WORD_1
	v_fmac_f32_e32 v111, v140, v32
	v_fmac_f32_e32 v111, v141, v33
	v_fmac_f32_e32 v111, v142, v34
	v_fmac_f32_e32 v111, v143, v35
	v_cvt_pk_f32_fp8_e32 v[140:141], v71
	v_cvt_pk_f32_fp8_sdwa v[142:143], v71 src0_sel:WORD_1
	v_fmac_f32_e32 v111, v140, v36
	v_fmac_f32_e32 v111, v141, v37
	v_fmac_f32_e32 v111, v142, v38
	v_fmac_f32_e32 v111, v143, v39
	s_waitcnt vmcnt(7)
	v_cvt_pk_f32_fp8_e32 v[140:141], v72
	v_cvt_pk_f32_fp8_sdwa v[142:143], v72 src0_sel:WORD_1
	v_mul_f32_e32 v112, v140, v24
	v_fmac_f32_e32 v112, v141, v25
	v_fmac_f32_e32 v112, v142, v26
	v_fmac_f32_e32 v112, v143, v27
	v_cvt_pk_f32_fp8_e32 v[140:141], v73
	v_cvt_pk_f32_fp8_sdwa v[142:143], v73 src0_sel:WORD_1
	v_fmac_f32_e32 v112, v140, v28
	v_fmac_f32_e32 v112, v141, v29
	v_fmac_f32_e32 v112, v142, v30
	v_fmac_f32_e32 v112, v143, v31
	v_cvt_pk_f32_fp8_e32 v[140:141], v74
	v_cvt_pk_f32_fp8_sdwa v[142:143], v74 src0_sel:WORD_1
	v_fmac_f32_e32 v112, v140, v32
	v_fmac_f32_e32 v112, v141, v33
	v_fmac_f32_e32 v112, v142, v34
	v_fmac_f32_e32 v112, v143, v35
	v_cvt_pk_f32_fp8_e32 v[140:141], v75
	v_cvt_pk_f32_fp8_sdwa v[142:143], v75 src0_sel:WORD_1
	v_fmac_f32_e32 v112, v140, v36
	v_fmac_f32_e32 v112, v141, v37
	v_fmac_f32_e32 v112, v142, v38
	v_fmac_f32_e32 v112, v143, v39
	s_waitcnt vmcnt(6)
	v_cvt_pk_f32_fp8_e32 v[140:141], v76
	v_cvt_pk_f32_fp8_sdwa v[142:143], v76 src0_sel:WORD_1
	v_mul_f32_e32 v113, v140, v24
	v_fmac_f32_e32 v113, v141, v25
	v_fmac_f32_e32 v113, v142, v26
	v_fmac_f32_e32 v113, v143, v27
	v_cvt_pk_f32_fp8_e32 v[140:141], v77
	v_cvt_pk_f32_fp8_sdwa v[142:143], v77 src0_sel:WORD_1
	v_fmac_f32_e32 v113, v140, v28
	v_fmac_f32_e32 v113, v141, v29
	v_fmac_f32_e32 v113, v142, v30
	v_fmac_f32_e32 v113, v143, v31
	v_cvt_pk_f32_fp8_e32 v[140:141], v78
	v_cvt_pk_f32_fp8_sdwa v[142:143], v78 src0_sel:WORD_1
	v_fmac_f32_e32 v113, v140, v32
	v_fmac_f32_e32 v113, v141, v33
	v_fmac_f32_e32 v113, v142, v34
	v_fmac_f32_e32 v113, v143, v35
	v_cvt_pk_f32_fp8_e32 v[140:141], v79
	v_cvt_pk_f32_fp8_sdwa v[142:143], v79 src0_sel:WORD_1
	v_fmac_f32_e32 v113, v140, v36
	v_fmac_f32_e32 v113, v141, v37
	v_fmac_f32_e32 v113, v142, v38
	v_fmac_f32_e32 v113, v143, v39
	s_waitcnt vmcnt(5)
	v_cvt_pk_f32_fp8_e32 v[140:141], v80
	v_cvt_pk_f32_fp8_sdwa v[142:143], v80 src0_sel:WORD_1
	v_mul_f32_e32 v114, v140, v24
	v_fmac_f32_e32 v114, v141, v25
	v_fmac_f32_e32 v114, v142, v26
	v_fmac_f32_e32 v114, v143, v27
	v_cvt_pk_f32_fp8_e32 v[140:141], v81
	v_cvt_pk_f32_fp8_sdwa v[142:143], v81 src0_sel:WORD_1
	v_fmac_f32_e32 v114, v140, v28
	v_fmac_f32_e32 v114, v141, v29
	v_fmac_f32_e32 v114, v142, v30
	v_fmac_f32_e32 v114, v143, v31
	v_cvt_pk_f32_fp8_e32 v[140:141], v82
	v_cvt_pk_f32_fp8_sdwa v[142:143], v82 src0_sel:WORD_1
	v_fmac_f32_e32 v114, v140, v32
	v_fmac_f32_e32 v114, v141, v33
	v_fmac_f32_e32 v114, v142, v34
	v_fmac_f32_e32 v114, v143, v35
	v_cvt_pk_f32_fp8_e32 v[140:141], v83
	v_cvt_pk_f32_fp8_sdwa v[142:143], v83 src0_sel:WORD_1
	v_fmac_f32_e32 v114, v140, v36
	v_fmac_f32_e32 v114, v141, v37
	v_fmac_f32_e32 v114, v142, v38
	v_fmac_f32_e32 v114, v143, v39
	s_waitcnt vmcnt(4)
	v_cvt_pk_f32_fp8_e32 v[140:141], v84
	v_cvt_pk_f32_fp8_sdwa v[142:143], v84 src0_sel:WORD_1
	v_mul_f32_e32 v115, v140, v24
	v_fmac_f32_e32 v115, v141, v25
	v_fmac_f32_e32 v115, v142, v26
	v_fmac_f32_e32 v115, v143, v27
	v_cvt_pk_f32_fp8_e32 v[140:141], v85
	v_cvt_pk_f32_fp8_sdwa v[142:143], v85 src0_sel:WORD_1
	v_fmac_f32_e32 v115, v140, v28
	v_fmac_f32_e32 v115, v141, v29
	v_fmac_f32_e32 v115, v142, v30
	v_fmac_f32_e32 v115, v143, v31
	v_cvt_pk_f32_fp8_e32 v[140:141], v86
	v_cvt_pk_f32_fp8_sdwa v[142:143], v86 src0_sel:WORD_1
	v_fmac_f32_e32 v115, v140, v32
	v_fmac_f32_e32 v115, v141, v33
	v_fmac_f32_e32 v115, v142, v34
	v_fmac_f32_e32 v115, v143, v35
	v_cvt_pk_f32_fp8_e32 v[140:141], v87
	v_cvt_pk_f32_fp8_sdwa v[142:143], v87 src0_sel:WORD_1
	v_fmac_f32_e32 v115, v140, v36
	v_fmac_f32_e32 v115, v141, v37
	v_fmac_f32_e32 v115, v142, v38
	v_fmac_f32_e32 v115, v143, v39
	s_waitcnt vmcnt(3)
	v_cvt_pk_f32_fp8_e32 v[140:141], v88
	v_cvt_pk_f32_fp8_sdwa v[142:143], v88 src0_sel:WORD_1
	v_mul_f32_e32 v116, v140, v24
	v_fmac_f32_e32 v116, v141, v25
	v_fmac_f32_e32 v116, v142, v26
	v_fmac_f32_e32 v116, v143, v27
	v_cvt_pk_f32_fp8_e32 v[140:141], v89
	v_cvt_pk_f32_fp8_sdwa v[142:143], v89 src0_sel:WORD_1
	v_fmac_f32_e32 v116, v140, v28
	v_fmac_f32_e32 v116, v141, v29
	v_fmac_f32_e32 v116, v142, v30
	v_fmac_f32_e32 v116, v143, v31
	v_cvt_pk_f32_fp8_e32 v[140:141], v90
	v_cvt_pk_f32_fp8_sdwa v[142:143], v90 src0_sel:WORD_1
	v_fmac_f32_e32 v116, v140, v32
	v_fmac_f32_e32 v116, v141, v33
	v_fmac_f32_e32 v116, v142, v34
	v_fmac_f32_e32 v116, v143, v35
	v_cvt_pk_f32_fp8_e32 v[140:141], v91
	v_cvt_pk_f32_fp8_sdwa v[142:143], v91 src0_sel:WORD_1
	v_fmac_f32_e32 v116, v140, v36
	v_fmac_f32_e32 v116, v141, v37
	v_fmac_f32_e32 v116, v142, v38
	v_fmac_f32_e32 v116, v143, v39
	s_waitcnt vmcnt(2)
	v_cvt_pk_f32_fp8_e32 v[140:141], v92
	v_cvt_pk_f32_fp8_sdwa v[142:143], v92 src0_sel:WORD_1
	v_mul_f32_e32 v117, v140, v24
	v_fmac_f32_e32 v117, v141, v25
	v_fmac_f32_e32 v117, v142, v26
	v_fmac_f32_e32 v117, v143, v27
	v_cvt_pk_f32_fp8_e32 v[140:141], v93
	v_cvt_pk_f32_fp8_sdwa v[142:143], v93 src0_sel:WORD_1
	v_fmac_f32_e32 v117, v140, v28
	v_fmac_f32_e32 v117, v141, v29
	v_fmac_f32_e32 v117, v142, v30
	v_fmac_f32_e32 v117, v143, v31
	v_cvt_pk_f32_fp8_e32 v[140:141], v94
	v_cvt_pk_f32_fp8_sdwa v[142:143], v94 src0_sel:WORD_1
	v_fmac_f32_e32 v117, v140, v32
	v_fmac_f32_e32 v117, v141, v33
	v_fmac_f32_e32 v117, v142, v34
	v_fmac_f32_e32 v117, v143, v35
	v_cvt_pk_f32_fp8_e32 v[140:141], v95
	v_cvt_pk_f32_fp8_sdwa v[142:143], v95 src0_sel:WORD_1
	v_fmac_f32_e32 v117, v140, v36
	v_fmac_f32_e32 v117, v141, v37
	v_fmac_f32_e32 v117, v142, v38
	v_fmac_f32_e32 v117, v143, v39
	s_waitcnt vmcnt(1)
	v_cvt_pk_f32_fp8_e32 v[140:141], v96
	v_cvt_pk_f32_fp8_sdwa v[142:143], v96 src0_sel:WORD_1
	v_mul_f32_e32 v118, v140, v24
	v_fmac_f32_e32 v118, v141, v25
	v_fmac_f32_e32 v118, v142, v26
	v_fmac_f32_e32 v118, v143, v27
	v_cvt_pk_f32_fp8_e32 v[140:141], v97
	v_cvt_pk_f32_fp8_sdwa v[142:143], v97 src0_sel:WORD_1
	v_fmac_f32_e32 v118, v140, v28
	v_fmac_f32_e32 v118, v141, v29
	v_fmac_f32_e32 v118, v142, v30
	v_fmac_f32_e32 v118, v143, v31
	v_cvt_pk_f32_fp8_e32 v[140:141], v98
	v_cvt_pk_f32_fp8_sdwa v[142:143], v98 src0_sel:WORD_1
	v_fmac_f32_e32 v118, v140, v32
	v_fmac_f32_e32 v118, v141, v33
	v_fmac_f32_e32 v118, v142, v34
	v_fmac_f32_e32 v118, v143, v35
	v_cvt_pk_f32_fp8_e32 v[140:141], v99
	v_cvt_pk_f32_fp8_sdwa v[142:143], v99 src0_sel:WORD_1
	v_fmac_f32_e32 v118, v140, v36
	v_fmac_f32_e32 v118, v141, v37
	v_fmac_f32_e32 v118, v142, v38
	v_fmac_f32_e32 v118, v143, v39
	s_waitcnt vmcnt(0)
	v_cvt_pk_f32_fp8_e32 v[140:141], v100
	v_cvt_pk_f32_fp8_sdwa v[142:143], v100 src0_sel:WORD_1
	v_mul_f32_e32 v119, v140, v24
	v_fmac_f32_e32 v119, v141, v25
	v_fmac_f32_e32 v119, v142, v26
	v_fmac_f32_e32 v119, v143, v27
	v_cvt_pk_f32_fp8_e32 v[140:141], v101
	v_cvt_pk_f32_fp8_sdwa v[142:143], v101 src0_sel:WORD_1
	v_fmac_f32_e32 v119, v140, v28
	v_fmac_f32_e32 v119, v141, v29
	v_fmac_f32_e32 v119, v142, v30
	v_fmac_f32_e32 v119, v143, v31
	v_cvt_pk_f32_fp8_e32 v[140:141], v102
	v_cvt_pk_f32_fp8_sdwa v[142:143], v102 src0_sel:WORD_1
	v_fmac_f32_e32 v119, v140, v32
	v_fmac_f32_e32 v119, v141, v33
	v_fmac_f32_e32 v119, v142, v34
	v_fmac_f32_e32 v119, v143, v35
	v_cvt_pk_f32_fp8_e32 v[140:141], v103
	v_cvt_pk_f32_fp8_sdwa v[142:143], v103 src0_sel:WORD_1
	v_fmac_f32_e32 v119, v140, v36
	v_fmac_f32_e32 v119, v141, v37
	v_fmac_f32_e32 v119, v142, v38
	v_fmac_f32_e32 v119, v143, v39
	s_waitcnt lgkmcnt(0)
.Lq_ured:
	v_cndmask_b32_e64 v144, v104, v112, s[36:37]
	v_cndmask_b32_e64 v152, v112, v104, s[36:37]
	v_cndmask_b32_e64 v145, v105, v113, s[36:37]
	v_cndmask_b32_e64 v153, v113, v105, s[36:37]
	v_cndmask_b32_e64 v146, v106, v114, s[36:37]
	v_cndmask_b32_e64 v154, v114, v106, s[36:37]
	v_cndmask_b32_e64 v147, v107, v115, s[36:37]
	v_cndmask_b32_e64 v155, v115, v107, s[36:37]
	v_cndmask_b32_e64 v148, v108, v116, s[36:37]
	v_cndmask_b32_e64 v156, v116, v108, s[36:37]
	v_cndmask_b32_e64 v149, v109, v117, s[36:37]
	v_cndmask_b32_e64 v157, v117, v109, s[36:37]
	v_cndmask_b32_e64 v150, v110, v118, s[36:37]
	v_cndmask_b32_e64 v158, v118, v110, s[36:37]
	v_cndmask_b32_e64 v151, v111, v119, s[36:37]
	v_cndmask_b32_e64 v159, v119, v111, s[36:37]
	v_add_f32_dpp v104, v152, v144 row_half_mirror row_mask:0xf bank_mask:0xf
	v_add_f32_dpp v105, v153, v145 row_half_mirror row_mask:0xf bank_mask:0xf
	v_add_f32_dpp v106, v154, v146 row_half_mirror row_mask:0xf bank_mask:0xf
	v_add_f32_dpp v107, v155, v147 row_half_mirror row_mask:0xf bank_mask:0xf
	v_add_f32_dpp v108, v156, v148 row_half_mirror row_mask:0xf bank_mask:0xf
	v_add_f32_dpp v109, v157, v149 row_half_mirror row_mask:0xf bank_mask:0xf
	v_add_f32_dpp v110, v158, v150 row_half_mirror row_mask:0xf bank_mask:0xf
	v_add_f32_dpp v111, v159, v151 row_half_mirror row_mask:0xf bank_mask:0xf
	v_cndmask_b32_e64 v144, v104, v108, s[38:39]
	v_cndmask_b32_e64 v152, v108, v104, s[38:39]
	v_cndmask_b32_e64 v145, v105, v109, s[38:39]
	v_cndmask_b32_e64 v153, v109, v105, s[38:39]
	v_cndmask_b32_e64 v146, v106, v110, s[38:39]
	v_cndmask_b32_e64 v154, v110, v106, s[38:39]
	v_cndmask_b32_e64 v147, v107, v111, s[38:39]
	v_cndmask_b32_e64 v155, v111, v107, s[38:39]
	s_nop 1
	v_add_f32_dpp v104, v152, v144 quad_perm:[2,3,0,1] row_mask:0xf bank_mask:0xf
	v_add_f32_dpp v105, v153, v145 quad_perm:[2,3,0,1] row_mask:0xf bank_mask:0xf
	v_add_f32_dpp v106, v154, v146 quad_perm:[2,3,0,1] row_mask:0xf bank_mask:0xf
	v_add_f32_dpp v107, v155, v147 quad_perm:[2,3,0,1] row_mask:0xf bank_mask:0xf
	v_cndmask_b32_e64 v144, v104, v106, s[16:17]
	v_cndmask_b32_e64 v152, v106, v104, s[16:17]
	v_cndmask_b32_e64 v145, v105, v107, s[16:17]
	v_cndmask_b32_e64 v153, v107, v105, s[16:17]
	s_nop 1
	v_add_f32_dpp v104, v152, v144 quad_perm:[1,0,3,2] row_mask:0xf bank_mask:0xf
	v_add_f32_dpp v105, v153, v145 quad_perm:[1,0,3,2] row_mask:0xf bank_mask:0xf
	s_cmp_eq_u32 s21, 0
	s_cselect_b64 vcc, -1, 0
	s_nop 1
	v_cndmask_b32_e64 v124, v124, 0, vcc
	v_cndmask_b32_e64 v125, v125, 0, vcc
	v_add_f32_e32 v124, v124, v104
	v_add_f32_e32 v125, v125, v105
	ds_write_b64 v122, v[124:125]
	s_add_i32 s14, s14, s26
	s_add_u32 s13, s13, 0x200
	s_add_u32 s100, s100, 1
	s_cmp_le_u32 s100, s12
	s_cbranch_scc1 .Lq_utok
	s_waitcnt lgkmcnt(0)
	s_add_i32 s8, s8, 1
	s_cmp_lt_u32 s8, 8
	s_cbranch_scc1 .Lq_upass
	s_mov_b32 s14, s101
	s_mov_b32 s13, 0
	s_mov_b32 s100, 0
.Lq_wgrp:
	s_mov_b32 s4, s14
	s_lshl_b32 s20, s4, 2
	s_add_u32 s20, s20, s15
	s_lshl_b32 s0, s20, 9
	s_add_u32 s1, s0, 0x28600000
	v_add_u32_e32 v120, s1, v203
	global_load_dwordx2 v[0:1], v120, s[6:7]
	s_add_u32 s1, s0, 0x29700000
	v_add_u32_e32 v121, s1, v203
	global_load_dwordx2 v[8:9], v121, s[6:7]
	s_add_i32 s4, s4, s26
	s_add_u32 s0, s100, 1
	s_cmp_ge_u32 s0, s12
	s_cbranch_scc1 .Lq_wl1
	s_lshl_b32 s20, s4, 2
	s_add_u32 s20, s20, s15
	s_lshl_b32 s0, s20, 9
	s_add_u32 s1, s0, 0x28600000
	v_add_u32_e32 v120, s1, v203
	global_load_dwordx2 v[2:3], v120, s[6:7]
	s_add_u32 s1, s0, 0x29700000
	v_add_u32_e32 v121, s1, v203
	global_load_dwordx2 v[10:11], v121, s[6:7]
	s_add_i32 s4, s4, s26
	s_add_u32 s0, s100, 2
	s_cmp_ge_u32 s0, s12
	s_cbranch_scc1 .Lq_wl1
	s_lshl_b32 s20, s4, 2
	s_add_u32 s20, s20, s15
	s_lshl_b32 s0, s20, 9
	s_add_u32 s1, s0, 0x28600000
	v_add_u32_e32 v120, s1, v203
	global_load_dwordx2 v[4:5], v120, s[6:7]
	s_add_u32 s1, s0, 0x29700000
	v_add_u32_e32 v121, s1, v203
	global_load_dwordx2 v[12:13], v121, s[6:7]
	s_add_i32 s4, s4, s26
	s_add_u32 s0, s100, 3
	s_cmp_ge_u32 s0, s12
	s_cbranch_scc1 .Lq_wl1
	s_lshl_b32 s20, s4, 2
	s_add_u32 s20, s20, s15
	s_lshl_b32 s0, s20, 9
	s_add_u32 s1, s0, 0x28600000
	v_add_u32_e32 v120, s1, v203
	global_load_dwordx2 v[6:7], v120, s[6:7]
	s_add_u32 s1, s0, 0x29700000
	v_add_u32_e32 v121, s1, v203
	global_load_dwordx2 v[14:15], v121, s[6:7]
	s_add_i32 s4, s4, s26
.Lq_wl1:
	s_waitcnt vmcnt(0)
	v_lshlrev_b32_e32 v120, 2, v0
	v_add_u32_e32 v121, 0x3907a000, v120
	v_add_u32_e32 v120, 0x3908a000, v120
	global_load_dword v16, v121, s[6:7]
	global_load_dword v24, v120, s[6:7]
	v_lshlrev_b32_e32 v120, 2, v1
	v_add_u32_e32 v121, 0x3907a000, v120
	v_add_u32_e32 v120, 0x3908a000, v120
	global_load_dword v17, v121, s[6:7]
	global_load_dword v25, v120, s[6:7]
	v_add_u32_e32 v122, s13, v198
	ds_read_b64 v[32:33], v122
	s_add_u32 s0, s100, 1
	s_cmp_ge_u32 s0, s12
	s_cbranch_scc1 .Lq_wl2
	v_lshlrev_b32_e32 v120, 2, v2
	v_add_u32_e32 v121, 0x3907a000, v120
	v_add_u32_e32 v120, 0x3908a000, v120
	global_load_dword v18, v121, s[6:7]
	global_load_dword v26, v120, s[6:7]
	v_lshlrev_b32_e32 v120, 2, v3
	v_add_u32_e32 v121, 0x3907a000, v120
	v_add_u32_e32 v120, 0x3908a000, v120
	global_load_dword v19, v121, s[6:7]
	global_load_dword v27, v120, s[6:7]
	v_add_u32_e32 v122, s13, v198
	ds_read_b64 v[34:35], v122 offset:512
	s_add_u32 s0, s100, 2
	s_cmp_ge_u32 s0, s12
	s_cbranch_scc1 .Lq_wl2
	v_lshlrev_b32_e32 v120, 2, v4
	v_add_u32_e32 v121, 0x3907a000, v120
	v_add_u32_e32 v120, 0x3908a000, v120
	global_load_dword v20, v121, s[6:7]
	global_load_dword v28, v120, s[6:7]
	v_lshlrev_b32_e32 v120, 2, v5
	v_add_u32_e32 v121, 0x3907a000, v120
	v_add_u32_e32 v120, 0x3908a000, v120
	global_load_dword v21, v121, s[6:7]
	global_load_dword v29, v120, s[6:7]
	v_add_u32_e32 v122, s13, v198
	ds_read_b64 v[36:37], v122 offset:1024
	s_add_u32 s0, s100, 3
	s_cmp_ge_u32 s0, s12
	s_cbranch_scc1 .Lq_wl2
	v_lshlrev_b32_e32 v120, 2, v6
	v_add_u32_e32 v121, 0x3907a000, v120
	v_add_u32_e32 v120, 0x3908a000, v120
	global_load_dword v22, v121, s[6:7]
	global_load_dword v30, v120, s[6:7]
	v_lshlrev_b32_e32 v120, 2, v7
	v_add_u32_e32 v121, 0x3907a000, v120
	v_add_u32_e32 v120, 0x3908a000, v120
	global_load_dword v23, v121, s[6:7]
	global_load_dword v31, v120, s[6:7]
	v_add_u32_e32 v122, s13, v198
	ds_read_b64 v[38:39], v122 offset:1536
.Lq_wl2:
	s_waitcnt vmcnt(0) lgkmcnt(0)
	s_mov_b32 s1, 0x7fffffff
	v_mul_f32_e32 v32, v32, v16
	v_mul_f32_e32 v144, 0x3f3504f3, v32
	v_and_b32_e32 v145, 0x7fffffff, v144
	v_mul_f32_e32 v146, v144, v144
	v_mov_b32_e32 v147, 0x3ba10414
	v_fmamk_f32 v147, v146, 0xba1345e1, v147
	v_fmaak_f32 v147, v146, v147, 0xbcdac9b8
	v_fmaak_f32 v147, v146, v147, 0x3de703be
	v_fmaak_f32 v147, v146, v147, 0xbec09330
	v_fmaak_f32 v147, v146, v147, 0x3e0375d0
	v_fma_f32 v147, v145, v147, v145
	v_mov_b32_e32 v148, 0xb9c68948
	v_fmamk_f32 v148, v145, 0x378e98ab, v148
	v_fmaak_f32 v148, v145, v148, 0x3b7cd369
	v_fmaak_f32 v148, v145, v148, 0xbcc618b2
	v_fmaak_f32 v148, v145, v148, 0x3dda74e4
	v_fmaak_f32 v148, v145, v148, 0x3f228afd
	v_fmaak_f32 v148, v145, v148, 0x3e03c728
	v_fma_f32 v148, v145, v148, v145
	v_mul_f32_e32 v149, 0xbfb8aa3b, v148
	v_exp_f32_e32 v149, v149
	v_cmp_gt_f32_e32 vcc, 1.0, v145
	v_sub_f32_e32 v150, 1.0, v149
	s_nop 0
	v_cndmask_b32_e32 v150, v150, v147, vcc
	v_bfi_b32 v150, s1, v150, v144
	v_mul_f32_e32 v32, 0.5, v32
	v_add_f32_e32 v150, 1.0, v150
	v_mul_f32_e32 v32, v32, v150
	v_mul_f32_e32 v32, v8, v32
	v_mul_f32_e32 v32, v32, v24
	v_mul_f32_e32 v33, v33, v17
	v_mul_f32_e32 v144, 0x3f3504f3, v33
	v_and_b32_e32 v145, 0x7fffffff, v144
	v_mul_f32_e32 v146, v144, v144
	v_mov_b32_e32 v147, 0x3ba10414
	v_fmamk_f32 v147, v146, 0xba1345e1, v147
	v_fmaak_f32 v147, v146, v147, 0xbcdac9b8
	v_fmaak_f32 v147, v146, v147, 0x3de703be
	v_fmaak_f32 v147, v146, v147, 0xbec09330
	v_fmaak_f32 v147, v146, v147, 0x3e0375d0
	v_fma_f32 v147, v145, v147, v145
	v_mov_b32_e32 v148, 0xb9c68948
	v_fmamk_f32 v148, v145, 0x378e98ab, v148
	v_fmaak_f32 v148, v145, v148, 0x3b7cd369
	v_fmaak_f32 v148, v145, v148, 0xbcc618b2
	v_fmaak_f32 v148, v145, v148, 0x3dda74e4
	v_fmaak_f32 v148, v145, v148, 0x3f228afd
	v_fmaak_f32 v148, v145, v148, 0x3e03c728
	v_fma_f32 v148, v145, v148, v145
	v_mul_f32_e32 v149, 0xbfb8aa3b, v148
	v_exp_f32_e32 v149, v149
	v_cmp_gt_f32_e32 vcc, 1.0, v145
	v_sub_f32_e32 v150, 1.0, v149
	s_nop 0
	v_cndmask_b32_e32 v150, v150, v147, vcc
	v_bfi_b32 v150, s1, v150, v144
	v_mul_f32_e32 v33, 0.5, v33
	v_add_f32_e32 v150, 1.0, v150
	v_mul_f32_e32 v33, v33, v150
	v_mul_f32_e32 v33, v9, v33
	v_mul_f32_e32 v33, v33, v25
	v_add_u32_e32 v122, s13, v198
	ds_write_b64 v122, v[32:33]
	s_add_u32 s0, s100, 1
	s_cmp_ge_u32 s0, s12
	s_cbranch_scc1 .Lq_wl3
	v_mul_f32_e32 v34, v34, v18
	v_mul_f32_e32 v144, 0x3f3504f3, v34
	v_and_b32_e32 v145, 0x7fffffff, v144
	v_mul_f32_e32 v146, v144, v144
	v_mov_b32_e32 v147, 0x3ba10414
	v_fmamk_f32 v147, v146, 0xba1345e1, v147
	v_fmaak_f32 v147, v146, v147, 0xbcdac9b8
	v_fmaak_f32 v147, v146, v147, 0x3de703be
	v_fmaak_f32 v147, v146, v147, 0xbec09330
	v_fmaak_f32 v147, v146, v147, 0x3e0375d0
	v_fma_f32 v147, v145, v147, v145
	v_mov_b32_e32 v148, 0xb9c68948
	v_fmamk_f32 v148, v145, 0x378e98ab, v148
	v_fmaak_f32 v148, v145, v148, 0x3b7cd369
	v_fmaak_f32 v148, v145, v148, 0xbcc618b2
	v_fmaak_f32 v148, v145, v148, 0x3dda74e4
	v_fmaak_f32 v148, v145, v148, 0x3f228afd
	v_fmaak_f32 v148, v145, v148, 0x3e03c728
	v_fma_f32 v148, v145, v148, v145
	v_mul_f32_e32 v149, 0xbfb8aa3b, v148
	v_exp_f32_e32 v149, v149
	v_cmp_gt_f32_e32 vcc, 1.0, v145
	v_sub_f32_e32 v150, 1.0, v149
	s_nop 0
	v_cndmask_b32_e32 v150, v150, v147, vcc
	v_bfi_b32 v150, s1, v150, v144
	v_mul_f32_e32 v34, 0.5, v34
	v_add_f32_e32 v150, 1.0, v150
	v_mul_f32_e32 v34, v34, v150
	v_mul_f32_e32 v34, v10, v34
	v_mul_f32_e32 v34, v34, v26
	v_mul_f32_e32 v35, v35, v19
	v_mul_f32_e32 v144, 0x3f3504f3, v35
	v_and_b32_e32 v145, 0x7fffffff, v144
	v_mul_f32_e32 v146, v144, v144
	v_mov_b32_e32 v147, 0x3ba10414
	v_fmamk_f32 v147, v146, 0xba1345e1, v147
	v_fmaak_f32 v147, v146, v147, 0xbcdac9b8
	v_fmaak_f32 v147, v146, v147, 0x3de703be
	v_fmaak_f32 v147, v146, v147, 0xbec09330
	v_fmaak_f32 v147, v146, v147, 0x3e0375d0
	v_fma_f32 v147, v145, v147, v145
	v_mov_b32_e32 v148, 0xb9c68948
	v_fmamk_f32 v148, v145, 0x378e98ab, v148
	v_fmaak_f32 v148, v145, v148, 0x3b7cd369
	v_fmaak_f32 v148, v145, v148, 0xbcc618b2
	v_fmaak_f32 v148, v145, v148, 0x3dda74e4
	v_fmaak_f32 v148, v145, v148, 0x3f228afd
	v_fmaak_f32 v148, v145, v148, 0x3e03c728
	v_fma_f32 v148, v145, v148, v145
	v_mul_f32_e32 v149, 0xbfb8aa3b, v148
	v_exp_f32_e32 v149, v149
	v_cmp_gt_f32_e32 vcc, 1.0, v145
	v_sub_f32_e32 v150, 1.0, v149
	s_nop 0
	v_cndmask_b32_e32 v150, v150, v147, vcc
	v_bfi_b32 v150, s1, v150, v144
	v_mul_f32_e32 v35, 0.5, v35
	v_add_f32_e32 v150, 1.0, v150
	v_mul_f32_e32 v35, v35, v150
	v_mul_f32_e32 v35, v11, v35
	v_mul_f32_e32 v35, v35, v27
	v_add_u32_e32 v122, s13, v198
	ds_write_b64 v122, v[34:35] offset:512
	s_add_u32 s0, s100, 2
	s_cmp_ge_u32 s0, s12
	s_cbranch_scc1 .Lq_wl3
	v_mul_f32_e32 v36, v36, v20
	v_mul_f32_e32 v144, 0x3f3504f3, v36
	v_and_b32_e32 v145, 0x7fffffff, v144
	v_mul_f32_e32 v146, v144, v144
	v_mov_b32_e32 v147, 0x3ba10414
	v_fmamk_f32 v147, v146, 0xba1345e1, v147
	v_fmaak_f32 v147, v146, v147, 0xbcdac9b8
	v_fmaak_f32 v147, v146, v147, 0x3de703be
	v_fmaak_f32 v147, v146, v147, 0xbec09330
	v_fmaak_f32 v147, v146, v147, 0x3e0375d0
	v_fma_f32 v147, v145, v147, v145
	v_mov_b32_e32 v148, 0xb9c68948
	v_fmamk_f32 v148, v145, 0x378e98ab, v148
	v_fmaak_f32 v148, v145, v148, 0x3b7cd369
	v_fmaak_f32 v148, v145, v148, 0xbcc618b2
	v_fmaak_f32 v148, v145, v148, 0x3dda74e4
	v_fmaak_f32 v148, v145, v148, 0x3f228afd
	v_fmaak_f32 v148, v145, v148, 0x3e03c728
	v_fma_f32 v148, v145, v148, v145
	v_mul_f32_e32 v149, 0xbfb8aa3b, v148
	v_exp_f32_e32 v149, v149
	v_cmp_gt_f32_e32 vcc, 1.0, v145
	v_sub_f32_e32 v150, 1.0, v149
	s_nop 0
	v_cndmask_b32_e32 v150, v150, v147, vcc
	v_bfi_b32 v150, s1, v150, v144
	v_mul_f32_e32 v36, 0.5, v36
	v_add_f32_e32 v150, 1.0, v150
	v_mul_f32_e32 v36, v36, v150
	v_mul_f32_e32 v36, v12, v36
	v_mul_f32_e32 v36, v36, v28
	v_mul_f32_e32 v37, v37, v21
	v_mul_f32_e32 v144, 0x3f3504f3, v37
	v_and_b32_e32 v145, 0x7fffffff, v144
	v_mul_f32_e32 v146, v144, v144
	v_mov_b32_e32 v147, 0x3ba10414
	v_fmamk_f32 v147, v146, 0xba1345e1, v147
	v_fmaak_f32 v147, v146, v147, 0xbcdac9b8
	v_fmaak_f32 v147, v146, v147, 0x3de703be
	v_fmaak_f32 v147, v146, v147, 0xbec09330
	v_fmaak_f32 v147, v146, v147, 0x3e0375d0
	v_fma_f32 v147, v145, v147, v145
	v_mov_b32_e32 v148, 0xb9c68948
	v_fmamk_f32 v148, v145, 0x378e98ab, v148
	v_fmaak_f32 v148, v145, v148, 0x3b7cd369
	v_fmaak_f32 v148, v145, v148, 0xbcc618b2
	v_fmaak_f32 v148, v145, v148, 0x3dda74e4
	v_fmaak_f32 v148, v145, v148, 0x3f228afd
	v_fmaak_f32 v148, v145, v148, 0x3e03c728
	v_fma_f32 v148, v145, v148, v145
	v_mul_f32_e32 v149, 0xbfb8aa3b, v148
	v_exp_f32_e32 v149, v149
	v_cmp_gt_f32_e32 vcc, 1.0, v145
	v_sub_f32_e32 v150, 1.0, v149
	s_nop 0
	v_cndmask_b32_e32 v150, v150, v147, vcc
	v_bfi_b32 v150, s1, v150, v144
	v_mul_f32_e32 v37, 0.5, v37
	v_add_f32_e32 v150, 1.0, v150
	v_mul_f32_e32 v37, v37, v150
	v_mul_f32_e32 v37, v13, v37
	v_mul_f32_e32 v37, v37, v29
	v_add_u32_e32 v122, s13, v198
	ds_write_b64 v122, v[36:37] offset:1024
	s_add_u32 s0, s100, 3
	s_cmp_ge_u32 s0, s12
	s_cbranch_scc1 .Lq_wl3
	v_mul_f32_e32 v38, v38, v22
	v_mul_f32_e32 v144, 0x3f3504f3, v38
	v_and_b32_e32 v145, 0x7fffffff, v144
	v_mul_f32_e32 v146, v144, v144
	v_mov_b32_e32 v147, 0x3ba10414
	v_fmamk_f32 v147, v146, 0xba1345e1, v147
	v_fmaak_f32 v147, v146, v147, 0xbcdac9b8
	v_fmaak_f32 v147, v146, v147, 0x3de703be
	v_fmaak_f32 v147, v146, v147, 0xbec09330
	v_fmaak_f32 v147, v146, v147, 0x3e0375d0
	v_fma_f32 v147, v145, v147, v145
	v_mov_b32_e32 v148, 0xb9c68948
	v_fmamk_f32 v148, v145, 0x378e98ab, v148
	v_fmaak_f32 v148, v145, v148, 0x3b7cd369
	v_fmaak_f32 v148, v145, v148, 0xbcc618b2
	v_fmaak_f32 v148, v145, v148, 0x3dda74e4
	v_fmaak_f32 v148, v145, v148, 0x3f228afd
	v_fmaak_f32 v148, v145, v148, 0x3e03c728
	v_fma_f32 v148, v145, v148, v145
	v_mul_f32_e32 v149, 0xbfb8aa3b, v148
	v_exp_f32_e32 v149, v149
	v_cmp_gt_f32_e32 vcc, 1.0, v145
	v_sub_f32_e32 v150, 1.0, v149
	s_nop 0
	v_cndmask_b32_e32 v150, v150, v147, vcc
	v_bfi_b32 v150, s1, v150, v144
	v_mul_f32_e32 v38, 0.5, v38
	v_add_f32_e32 v150, 1.0, v150
	v_mul_f32_e32 v38, v38, v150
	v_mul_f32_e32 v38, v14, v38
	v_mul_f32_e32 v38, v38, v30
	v_mul_f32_e32 v39, v39, v23
	v_mul_f32_e32 v144, 0x3f3504f3, v39
	v_and_b32_e32 v145, 0x7fffffff, v144
	v_mul_f32_e32 v146, v144, v144
	v_mov_b32_e32 v147, 0x3ba10414
	v_fmamk_f32 v147, v146, 0xba1345e1, v147
	v_fmaak_f32 v147, v146, v147, 0xbcdac9b8
	v_fmaak_f32 v147, v146, v147, 0x3de703be
	v_fmaak_f32 v147, v146, v147, 0xbec09330
	v_fmaak_f32 v147, v146, v147, 0x3e0375d0
	v_fma_f32 v147, v145, v147, v145
	v_mov_b32_e32 v148, 0xb9c68948
	v_fmamk_f32 v148, v145, 0x378e98ab, v148
	v_fmaak_f32 v148, v145, v148, 0x3b7cd369
	v_fmaak_f32 v148, v145, v148, 0xbcc618b2
	v_fmaak_f32 v148, v145, v148, 0x3dda74e4
	v_fmaak_f32 v148, v145, v148, 0x3f228afd
	v_fmaak_f32 v148, v145, v148, 0x3e03c728
	v_fma_f32 v148, v145, v148, v145
	v_mul_f32_e32 v149, 0xbfb8aa3b, v148
	v_exp_f32_e32 v149, v149
	v_cmp_gt_f32_e32 vcc, 1.0, v145
	v_sub_f32_e32 v150, 1.0, v149
	s_nop 0
	v_cndmask_b32_e32 v150, v150, v147, vcc
	v_bfi_b32 v150, s1, v150, v144
	v_mul_f32_e32 v39, 0.5, v39
	v_add_f32_e32 v150, 1.0, v150
	v_mul_f32_e32 v39, v39, v150
	v_mul_f32_e32 v39, v15, v39
	v_mul_f32_e32 v39, v39, v31
	v_add_u32_e32 v122, s13, v198
	ds_write_b64 v122, v[38:39] offset:1536
.Lq_wl3:
	s_mov_b32 s14, s4
	s_add_u32 s13, s13, 0x800
	s_add_u32 s100, s100, 4
	s_cmp_lt_u32 s100, s12
	s_cbranch_scc1 .Lq_wgrp
	s_waitcnt lgkmcnt(0)
.Lq_vpass:
	s_sub_i32 s21, s8, 8
	s_lshl_b32 s4, s21, 7
	s_add_u32 s4, s4, 0x36500000
	v_add_u32_e32 v123, s4, v200
	s_mul_i32 s5, s2, 0x36000
	s_lshl_b32 s4, s21, 9
	s_add_u32 s5, s5, s4
	s_add_u32 s5, s5, 0x388e5000
	s_mov_b32 s14, s101
	s_mov_b32 s13, 0
	s_mov_b32 s100, 1
	v_add_u32_e32 v120, s13, v207
	ds_read_b128 v[0:3], v120
	ds_read_b128 v[4:7], v120 offset:16
	ds_read_b128 v[8:11], v120 offset:32
	ds_read_b128 v[12:15], v120 offset:48
	s_waitcnt lgkmcnt(0)
	v_lshl_add_u32 v0, v0, 10, v123
	v_lshl_add_u32 v1, v1, 10, v123
	v_lshl_add_u32 v2, v2, 10, v123
	v_lshl_add_u32 v3, v3, 10, v123
	v_lshl_add_u32 v4, v4, 10, v123
	v_lshl_add_u32 v5, v5, 10, v123
	v_lshl_add_u32 v6, v6, 10, v123
	v_lshl_add_u32 v7, v7, 10, v123
	v_lshl_add_u32 v8, v8, 10, v123
	v_lshl_add_u32 v9, v9, 10, v123
	v_lshl_add_u32 v10, v10, 10, v123
	v_lshl_add_u32 v11, v11, 10, v123
	v_lshl_add_u32 v12, v12, 10, v123
	v_lshl_add_u32 v13, v13, 10, v123
	v_lshl_add_u32 v14, v14, 10, v123
	v_lshl_add_u32 v15, v15, 10, v123
	global_load_dwordx4 v[40:43], v0, s[6:7]
	global_load_dwordx4 v[44:47], v1, s[6:7]
	global_load_dwordx4 v[48:51], v2, s[6:7]
	global_load_dwordx4 v[52:55], v3, s[6:7]
	global_load_dwordx4 v[56:59], v4, s[6:7]
	global_load_dwordx4 v[60:63], v5, s[6:7]
	global_load_dwordx4 v[64:67], v6, s[6:7]
	global_load_dwordx4 v[68:71], v7, s[6:7]
	global_load_dwordx4 v[72:75], v8, s[6:7]
	global_load_dwordx4 v[76:79], v9, s[6:7]
	global_load_dwordx4 v[80:83], v10, s[6:7]
	global_load_dwordx4 v[84:87], v11, s[6:7]
	global_load_dwordx4 v[88:91], v12, s[6:7]
	global_load_dwordx4 v[92:95], v13, s[6:7]
	global_load_dwordx4 v[96:99], v14, s[6:7]
	global_load_dwordx4 v[100:103], v15, s[6:7]
.Lq_vtok:
	s_lshl_b32 s20, s14, 2
	s_add_u32 s20, s20, s15
	v_add_u32_e32 v120, s13, v197
	ds_read_b128 v[16:19], v120
	ds_read_b128 v[20:23], v120 offset:16
	ds_read_b128 v[24:27], v120 offset:32
	ds_read_b128 v[28:31], v120 offset:48
	s_lshl_b32 s1, s20, 12
	s_lshl_b32 s4, s21, 9
	s_add_u32 s1, s1, s4
	v_add_u32_e32 v199, s1, v204
	global_load_dwordx2 v[124:125], v199, s[6:7]
	s_lshr_b32 s0, s20, 12
	s_cmp_ge_u32 s20, 0x8000
	s_cselect_b32 s0, 8, s0
	s_mul_i32 s0, s0, 0x6000
	s_add_u32 s0, s0, s5
	v_add_u32_e32 v121, s0, v204
	global_load_dwordx2 v[126:127], v121, s[6:7]
	s_cmp_ge_u32 s100, s12
	s_cbranch_scc1 .Lq_vlast
	s_add_u32 s0, s13, 0x200
	v_add_u32_e32 v120, s0, v207
	ds_read_b128 v[0:3], v120
	ds_read_b128 v[4:7], v120 offset:16
	ds_read_b128 v[8:11], v120 offset:32
	ds_read_b128 v[12:15], v120 offset:48
	s_waitcnt lgkmcnt(4)
	s_waitcnt vmcnt(17)
	v_cvt_pk_f32_fp8_e32 v[140:141], v40
	v_cvt_pk_f32_fp8_sdwa v[142:143], v40 src0_sel:WORD_1
	v_mul_f32_e32 v104, v16, v140
	v_mul_f32_e32 v105, v16, v141
	v_mul_f32_e32 v106, v16, v142
	v_mul_f32_e32 v107, v16, v143
	v_cvt_pk_f32_fp8_e32 v[140:141], v41
	v_cvt_pk_f32_fp8_sdwa v[142:143], v41 src0_sel:WORD_1
	v_mul_f32_e32 v108, v16, v140
	v_mul_f32_e32 v109, v16, v141
	v_mul_f32_e32 v110, v16, v142
	v_mul_f32_e32 v111, v16, v143
	v_cvt_pk_f32_fp8_e32 v[140:141], v42
	v_cvt_pk_f32_fp8_sdwa v[142:143], v42 src0_sel:WORD_1
	v_mul_f32_e32 v112, v16, v140
	v_mul_f32_e32 v113, v16, v141
	v_mul_f32_e32 v114, v16, v142
	v_mul_f32_e32 v115, v16, v143
	v_cvt_pk_f32_fp8_e32 v[140:141], v43
	v_cvt_pk_f32_fp8_sdwa v[142:143], v43 src0_sel:WORD_1
	v_mul_f32_e32 v116, v16, v140
	v_mul_f32_e32 v117, v16, v141
	v_mul_f32_e32 v118, v16, v142
	v_mul_f32_e32 v119, v16, v143
	s_waitcnt vmcnt(16)
	v_cvt_pk_f32_fp8_e32 v[140:141], v44
	v_cvt_pk_f32_fp8_sdwa v[142:143], v44 src0_sel:WORD_1
	v_fmac_f32_e32 v104, v17, v140
	v_fmac_f32_e32 v105, v17, v141
	v_fmac_f32_e32 v106, v17, v142
	v_fmac_f32_e32 v107, v17, v143
	v_cvt_pk_f32_fp8_e32 v[140:141], v45
	v_cvt_pk_f32_fp8_sdwa v[142:143], v45 src0_sel:WORD_1
	v_fmac_f32_e32 v108, v17, v140
	v_fmac_f32_e32 v109, v17, v141
	v_fmac_f32_e32 v110, v17, v142
	v_fmac_f32_e32 v111, v17, v143
	v_cvt_pk_f32_fp8_e32 v[140:141], v46
	v_cvt_pk_f32_fp8_sdwa v[142:143], v46 src0_sel:WORD_1
	v_fmac_f32_e32 v112, v17, v140
	v_fmac_f32_e32 v113, v17, v141
	v_fmac_f32_e32 v114, v17, v142
	v_fmac_f32_e32 v115, v17, v143
	v_cvt_pk_f32_fp8_e32 v[140:141], v47
	v_cvt_pk_f32_fp8_sdwa v[142:143], v47 src0_sel:WORD_1
	v_fmac_f32_e32 v116, v17, v140
	v_fmac_f32_e32 v117, v17, v141
	v_fmac_f32_e32 v118, v17, v142
	v_fmac_f32_e32 v119, v17, v143
	s_waitcnt vmcnt(15)
	v_cvt_pk_f32_fp8_e32 v[140:141], v48
	v_cvt_pk_f32_fp8_sdwa v[142:143], v48 src0_sel:WORD_1
	v_fmac_f32_e32 v104, v18, v140
	v_fmac_f32_e32 v105, v18, v141
	v_fmac_f32_e32 v106, v18, v142
	v_fmac_f32_e32 v107, v18, v143
	v_cvt_pk_f32_fp8_e32 v[140:141], v49
	v_cvt_pk_f32_fp8_sdwa v[142:143], v49 src0_sel:WORD_1
	v_fmac_f32_e32 v108, v18, v140
	v_fmac_f32_e32 v109, v18, v141
	v_fmac_f32_e32 v110, v18, v142
	v_fmac_f32_e32 v111, v18, v143
	v_cvt_pk_f32_fp8_e32 v[140:141], v50
	v_cvt_pk_f32_fp8_sdwa v[142:143], v50 src0_sel:WORD_1
	v_fmac_f32_e32 v112, v18, v140
	v_fmac_f32_e32 v113, v18, v141
	v_fmac_f32_e32 v114, v18, v142
	v_fmac_f32_e32 v115, v18, v143
	v_cvt_pk_f32_fp8_e32 v[140:141], v51
	v_cvt_pk_f32_fp8_sdwa v[142:143], v51 src0_sel:WORD_1
	v_fmac_f32_e32 v116, v18, v140
	v_fmac_f32_e32 v117, v18, v141
	v_fmac_f32_e32 v118, v18, v142
	v_fmac_f32_e32 v119, v18, v143
	s_waitcnt vmcnt(14)
	v_cvt_pk_f32_fp8_e32 v[140:141], v52
	v_cvt_pk_f32_fp8_sdwa v[142:143], v52 src0_sel:WORD_1
	v_fmac_f32_e32 v104, v19, v140
	v_fmac_f32_e32 v105, v19, v141
	v_fmac_f32_e32 v106, v19, v142
	v_fmac_f32_e32 v107, v19, v143
	v_cvt_pk_f32_fp8_e32 v[140:141], v53
	v_cvt_pk_f32_fp8_sdwa v[142:143], v53 src0_sel:WORD_1
	v_fmac_f32_e32 v108, v19, v140
	v_fmac_f32_e32 v109, v19, v141
	v_fmac_f32_e32 v110, v19, v142
	v_fmac_f32_e32 v111, v19, v143
	v_cvt_pk_f32_fp8_e32 v[140:141], v54
	v_cvt_pk_f32_fp8_sdwa v[142:143], v54 src0_sel:WORD_1
	v_fmac_f32_e32 v112, v19, v140
	v_fmac_f32_e32 v113, v19, v141
	v_fmac_f32_e32 v114, v19, v142
	v_fmac_f32_e32 v115, v19, v143
	v_cvt_pk_f32_fp8_e32 v[140:141], v55
	v_cvt_pk_f32_fp8_sdwa v[142:143], v55 src0_sel:WORD_1
	v_fmac_f32_e32 v116, v19, v140
	v_fmac_f32_e32 v117, v19, v141
	v_fmac_f32_e32 v118, v19, v142
	v_fmac_f32_e32 v119, v19, v143
	s_waitcnt vmcnt(13)
	v_cvt_pk_f32_fp8_e32 v[140:141], v56
	v_cvt_pk_f32_fp8_sdwa v[142:143], v56 src0_sel:WORD_1
	v_fmac_f32_e32 v104, v20, v140
	v_fmac_f32_e32 v105, v20, v141
	v_fmac_f32_e32 v106, v20, v142
	v_fmac_f32_e32 v107, v20, v143
	v_cvt_pk_f32_fp8_e32 v[140:141], v57
	v_cvt_pk_f32_fp8_sdwa v[142:143], v57 src0_sel:WORD_1
	v_fmac_f32_e32 v108, v20, v140
	v_fmac_f32_e32 v109, v20, v141
	v_fmac_f32_e32 v110, v20, v142
	v_fmac_f32_e32 v111, v20, v143
	v_cvt_pk_f32_fp8_e32 v[140:141], v58
	v_cvt_pk_f32_fp8_sdwa v[142:143], v58 src0_sel:WORD_1
	v_fmac_f32_e32 v112, v20, v140
	v_fmac_f32_e32 v113, v20, v141
	v_fmac_f32_e32 v114, v20, v142
	v_fmac_f32_e32 v115, v20, v143
	v_cvt_pk_f32_fp8_e32 v[140:141], v59
	v_cvt_pk_f32_fp8_sdwa v[142:143], v59 src0_sel:WORD_1
	v_fmac_f32_e32 v116, v20, v140
	v_fmac_f32_e32 v117, v20, v141
	v_fmac_f32_e32 v118, v20, v142
	v_fmac_f32_e32 v119, v20, v143
	s_waitcnt vmcnt(12)
	v_cvt_pk_f32_fp8_e32 v[140:141], v60
	v_cvt_pk_f32_fp8_sdwa v[142:143], v60 src0_sel:WORD_1
	v_fmac_f32_e32 v104, v21, v140
	v_fmac_f32_e32 v105, v21, v141
	v_fmac_f32_e32 v106, v21, v142
	v_fmac_f32_e32 v107, v21, v143
	v_cvt_pk_f32_fp8_e32 v[140:141], v61
	v_cvt_pk_f32_fp8_sdwa v[142:143], v61 src0_sel:WORD_1
	v_fmac_f32_e32 v108, v21, v140
	v_fmac_f32_e32 v109, v21, v141
	v_fmac_f32_e32 v110, v21, v142
	v_fmac_f32_e32 v111, v21, v143
	v_cvt_pk_f32_fp8_e32 v[140:141], v62
	v_cvt_pk_f32_fp8_sdwa v[142:143], v62 src0_sel:WORD_1
	v_fmac_f32_e32 v112, v21, v140
	v_fmac_f32_e32 v113, v21, v141
	v_fmac_f32_e32 v114, v21, v142
	v_fmac_f32_e32 v115, v21, v143
	v_cvt_pk_f32_fp8_e32 v[140:141], v63
	v_cvt_pk_f32_fp8_sdwa v[142:143], v63 src0_sel:WORD_1
	v_fmac_f32_e32 v116, v21, v140
	v_fmac_f32_e32 v117, v21, v141
	v_fmac_f32_e32 v118, v21, v142
	v_fmac_f32_e32 v119, v21, v143
	s_waitcnt vmcnt(11)
	v_cvt_pk_f32_fp8_e32 v[140:141], v64
	v_cvt_pk_f32_fp8_sdwa v[142:143], v64 src0_sel:WORD_1
	v_fmac_f32_e32 v104, v22, v140
	v_fmac_f32_e32 v105, v22, v141
	v_fmac_f32_e32 v106, v22, v142
	v_fmac_f32_e32 v107, v22, v143
	v_cvt_pk_f32_fp8_e32 v[140:141], v65
	v_cvt_pk_f32_fp8_sdwa v[142:143], v65 src0_sel:WORD_1
	v_fmac_f32_e32 v108, v22, v140
	v_fmac_f32_e32 v109, v22, v141
	v_fmac_f32_e32 v110, v22, v142
	v_fmac_f32_e32 v111, v22, v143
	v_cvt_pk_f32_fp8_e32 v[140:141], v66
	v_cvt_pk_f32_fp8_sdwa v[142:143], v66 src0_sel:WORD_1
	v_fmac_f32_e32 v112, v22, v140
	v_fmac_f32_e32 v113, v22, v141
	v_fmac_f32_e32 v114, v22, v142
	v_fmac_f32_e32 v115, v22, v143
	v_cvt_pk_f32_fp8_e32 v[140:141], v67
	v_cvt_pk_f32_fp8_sdwa v[142:143], v67 src0_sel:WORD_1
	v_fmac_f32_e32 v116, v22, v140
	v_fmac_f32_e32 v117, v22, v141
	v_fmac_f32_e32 v118, v22, v142
	v_fmac_f32_e32 v119, v22, v143
	s_waitcnt vmcnt(10)
	v_cvt_pk_f32_fp8_e32 v[140:141], v68
	v_cvt_pk_f32_fp8_sdwa v[142:143], v68 src0_sel:WORD_1
	v_fmac_f32_e32 v104, v23, v140
	v_fmac_f32_e32 v105, v23, v141
	v_fmac_f32_e32 v106, v23, v142
	v_fmac_f32_e32 v107, v23, v143
	v_cvt_pk_f32_fp8_e32 v[140:141], v69
	v_cvt_pk_f32_fp8_sdwa v[142:143], v69 src0_sel:WORD_1
	v_fmac_f32_e32 v108, v23, v140
	v_fmac_f32_e32 v109, v23, v141
	v_fmac_f32_e32 v110, v23, v142
	v_fmac_f32_e32 v111, v23, v143
	v_cvt_pk_f32_fp8_e32 v[140:141], v70
	v_cvt_pk_f32_fp8_sdwa v[142:143], v70 src0_sel:WORD_1
	v_fmac_f32_e32 v112, v23, v140
	v_fmac_f32_e32 v113, v23, v141
	v_fmac_f32_e32 v114, v23, v142
	v_fmac_f32_e32 v115, v23, v143
	v_cvt_pk_f32_fp8_e32 v[140:141], v71
	v_cvt_pk_f32_fp8_sdwa v[142:143], v71 src0_sel:WORD_1
	v_fmac_f32_e32 v116, v23, v140
	v_fmac_f32_e32 v117, v23, v141
	v_fmac_f32_e32 v118, v23, v142
	v_fmac_f32_e32 v119, v23, v143
	s_waitcnt lgkmcnt(0)
	v_lshl_add_u32 v0, v0, 10, v123
	v_lshl_add_u32 v1, v1, 10, v123
	v_lshl_add_u32 v2, v2, 10, v123
	v_lshl_add_u32 v3, v3, 10, v123
	v_lshl_add_u32 v4, v4, 10, v123
	v_lshl_add_u32 v5, v5, 10, v123
	v_lshl_add_u32 v6, v6, 10, v123
	v_lshl_add_u32 v7, v7, 10, v123
	v_lshl_add_u32 v8, v8, 10, v123
	v_lshl_add_u32 v9, v9, 10, v123
	v_lshl_add_u32 v10, v10, 10, v123
	v_lshl_add_u32 v11, v11, 10, v123
	v_lshl_add_u32 v12, v12, 10, v123
	v_lshl_add_u32 v13, v13, 10, v123
	v_lshl_add_u32 v14, v14, 10, v123
	v_lshl_add_u32 v15, v15, 10, v123
	global_load_dwordx4 v[40:43], v0, s[6:7]
	global_load_dwordx4 v[44:47], v1, s[6:7]
	global_load_dwordx4 v[48:51], v2, s[6:7]
	global_load_dwordx4 v[52:55], v3, s[6:7]
	global_load_dwordx4 v[56:59], v4, s[6:7]
	global_load_dwordx4 v[60:63], v5, s[6:7]
	global_load_dwordx4 v[64:67], v6, s[6:7]
	global_load_dwordx4 v[68:71], v7, s[6:7]
	s_waitcnt vmcnt(17)
	v_cvt_pk_f32_fp8_e32 v[140:141], v72
	v_cvt_pk_f32_fp8_sdwa v[142:143], v72 src0_sel:WORD_1
	v_fmac_f32_e32 v104, v24, v140
	v_fmac_f32_e32 v105, v24, v141
	v_fmac_f32_e32 v106, v24, v142
	v_fmac_f32_e32 v107, v24, v143
	v_cvt_pk_f32_fp8_e32 v[140:141], v73
	v_cvt_pk_f32_fp8_sdwa v[142:143], v73 src0_sel:WORD_1
	v_fmac_f32_e32 v108, v24, v140
	v_fmac_f32_e32 v109, v24, v141
	v_fmac_f32_e32 v110, v24, v142
	v_fmac_f32_e32 v111, v24, v143
	v_cvt_pk_f32_fp8_e32 v[140:141], v74
	v_cvt_pk_f32_fp8_sdwa v[142:143], v74 src0_sel:WORD_1
	v_fmac_f32_e32 v112, v24, v140
	v_fmac_f32_e32 v113, v24, v141
	v_fmac_f32_e32 v114, v24, v142
	v_fmac_f32_e32 v115, v24, v143
	v_cvt_pk_f32_fp8_e32 v[140:141], v75
	v_cvt_pk_f32_fp8_sdwa v[142:143], v75 src0_sel:WORD_1
	v_fmac_f32_e32 v116, v24, v140
	v_fmac_f32_e32 v117, v24, v141
	v_fmac_f32_e32 v118, v24, v142
	v_fmac_f32_e32 v119, v24, v143
	s_waitcnt vmcnt(16)
	v_cvt_pk_f32_fp8_e32 v[140:141], v76
	v_cvt_pk_f32_fp8_sdwa v[142:143], v76 src0_sel:WORD_1
	v_fmac_f32_e32 v104, v25, v140
	v_fmac_f32_e32 v105, v25, v141
	v_fmac_f32_e32 v106, v25, v142
	v_fmac_f32_e32 v107, v25, v143
	v_cvt_pk_f32_fp8_e32 v[140:141], v77
	v_cvt_pk_f32_fp8_sdwa v[142:143], v77 src0_sel:WORD_1
	v_fmac_f32_e32 v108, v25, v140
	v_fmac_f32_e32 v109, v25, v141
	v_fmac_f32_e32 v110, v25, v142
	v_fmac_f32_e32 v111, v25, v143
	v_cvt_pk_f32_fp8_e32 v[140:141], v78
	v_cvt_pk_f32_fp8_sdwa v[142:143], v78 src0_sel:WORD_1
	v_fmac_f32_e32 v112, v25, v140
	v_fmac_f32_e32 v113, v25, v141
	v_fmac_f32_e32 v114, v25, v142
	v_fmac_f32_e32 v115, v25, v143
	v_cvt_pk_f32_fp8_e32 v[140:141], v79
	v_cvt_pk_f32_fp8_sdwa v[142:143], v79 src0_sel:WORD_1
	v_fmac_f32_e32 v116, v25, v140
	v_fmac_f32_e32 v117, v25, v141
	v_fmac_f32_e32 v118, v25, v142
	v_fmac_f32_e32 v119, v25, v143
	s_waitcnt vmcnt(15)
	v_cvt_pk_f32_fp8_e32 v[140:141], v80
	v_cvt_pk_f32_fp8_sdwa v[142:143], v80 src0_sel:WORD_1
	v_fmac_f32_e32 v104, v26, v140
	v_fmac_f32_e32 v105, v26, v141
	v_fmac_f32_e32 v106, v26, v142
	v_fmac_f32_e32 v107, v26, v143
	v_cvt_pk_f32_fp8_e32 v[140:141], v81
	v_cvt_pk_f32_fp8_sdwa v[142:143], v81 src0_sel:WORD_1
	v_fmac_f32_e32 v108, v26, v140
	v_fmac_f32_e32 v109, v26, v141
	v_fmac_f32_e32 v110, v26, v142
	v_fmac_f32_e32 v111, v26, v143
	v_cvt_pk_f32_fp8_e32 v[140:141], v82
	v_cvt_pk_f32_fp8_sdwa v[142:143], v82 src0_sel:WORD_1
	v_fmac_f32_e32 v112, v26, v140
	v_fmac_f32_e32 v113, v26, v141
	v_fmac_f32_e32 v114, v26, v142
	v_fmac_f32_e32 v115, v26, v143
	v_cvt_pk_f32_fp8_e32 v[140:141], v83
	v_cvt_pk_f32_fp8_sdwa v[142:143], v83 src0_sel:WORD_1
	v_fmac_f32_e32 v116, v26, v140
	v_fmac_f32_e32 v117, v26, v141
	v_fmac_f32_e32 v118, v26, v142
	v_fmac_f32_e32 v119, v26, v143
	s_waitcnt vmcnt(14)
	v_cvt_pk_f32_fp8_e32 v[140:141], v84
	v_cvt_pk_f32_fp8_sdwa v[142:143], v84 src0_sel:WORD_1
	v_fmac_f32_e32 v104, v27, v140
	v_fmac_f32_e32 v105, v27, v141
	v_fmac_f32_e32 v106, v27, v142
	v_fmac_f32_e32 v107, v27, v143
	v_cvt_pk_f32_fp8_e32 v[140:141], v85
	v_cvt_pk_f32_fp8_sdwa v[142:143], v85 src0_sel:WORD_1
	v_fmac_f32_e32 v108, v27, v140
	v_fmac_f32_e32 v109, v27, v141
	v_fmac_f32_e32 v110, v27, v142
	v_fmac_f32_e32 v111, v27, v143
	v_cvt_pk_f32_fp8_e32 v[140:141], v86
	v_cvt_pk_f32_fp8_sdwa v[142:143], v86 src0_sel:WORD_1
	v_fmac_f32_e32 v112, v27, v140
	v_fmac_f32_e32 v113, v27, v141
	v_fmac_f32_e32 v114, v27, v142
	v_fmac_f32_e32 v115, v27, v143
	v_cvt_pk_f32_fp8_e32 v[140:141], v87
	v_cvt_pk_f32_fp8_sdwa v[142:143], v87 src0_sel:WORD_1
	v_fmac_f32_e32 v116, v27, v140
	v_fmac_f32_e32 v117, v27, v141
	v_fmac_f32_e32 v118, v27, v142
	v_fmac_f32_e32 v119, v27, v143
	s_waitcnt vmcnt(13)
	v_cvt_pk_f32_fp8_e32 v[140:141], v88
	v_cvt_pk_f32_fp8_sdwa v[142:143], v88 src0_sel:WORD_1
	v_fmac_f32_e32 v104, v28, v140
	v_fmac_f32_e32 v105, v28, v141
	v_fmac_f32_e32 v106, v28, v142
	v_fmac_f32_e32 v107, v28, v143
	v_cvt_pk_f32_fp8_e32 v[140:141], v89
	v_cvt_pk_f32_fp8_sdwa v[142:143], v89 src0_sel:WORD_1
	v_fmac_f32_e32 v108, v28, v140
	v_fmac_f32_e32 v109, v28, v141
	v_fmac_f32_e32 v110, v28, v142
	v_fmac_f32_e32 v111, v28, v143
	v_cvt_pk_f32_fp8_e32 v[140:141], v90
	v_cvt_pk_f32_fp8_sdwa v[142:143], v90 src0_sel:WORD_1
	v_fmac_f32_e32 v112, v28, v140
	v_fmac_f32_e32 v113, v28, v141
	v_fmac_f32_e32 v114, v28, v142
	v_fmac_f32_e32 v115, v28, v143
	v_cvt_pk_f32_fp8_e32 v[140:141], v91
	v_cvt_pk_f32_fp8_sdwa v[142:143], v91 src0_sel:WORD_1
	v_fmac_f32_e32 v116, v28, v140
	v_fmac_f32_e32 v117, v28, v141
	v_fmac_f32_e32 v118, v28, v142
	v_fmac_f32_e32 v119, v28, v143
	s_waitcnt vmcnt(12)
	v_cvt_pk_f32_fp8_e32 v[140:141], v92
	v_cvt_pk_f32_fp8_sdwa v[142:143], v92 src0_sel:WORD_1
	v_fmac_f32_e32 v104, v29, v140
	v_fmac_f32_e32 v105, v29, v141
	v_fmac_f32_e32 v106, v29, v142
	v_fmac_f32_e32 v107, v29, v143
	v_cvt_pk_f32_fp8_e32 v[140:141], v93
	v_cvt_pk_f32_fp8_sdwa v[142:143], v93 src0_sel:WORD_1
	v_fmac_f32_e32 v108, v29, v140
	v_fmac_f32_e32 v109, v29, v141
	v_fmac_f32_e32 v110, v29, v142
	v_fmac_f32_e32 v111, v29, v143
	v_cvt_pk_f32_fp8_e32 v[140:141], v94
	v_cvt_pk_f32_fp8_sdwa v[142:143], v94 src0_sel:WORD_1
	v_fmac_f32_e32 v112, v29, v140
	v_fmac_f32_e32 v113, v29, v141
	v_fmac_f32_e32 v114, v29, v142
	v_fmac_f32_e32 v115, v29, v143
	v_cvt_pk_f32_fp8_e32 v[140:141], v95
	v_cvt_pk_f32_fp8_sdwa v[142:143], v95 src0_sel:WORD_1
	v_fmac_f32_e32 v116, v29, v140
	v_fmac_f32_e32 v117, v29, v141
	v_fmac_f32_e32 v118, v29, v142
	v_fmac_f32_e32 v119, v29, v143
	s_waitcnt vmcnt(11)
	v_cvt_pk_f32_fp8_e32 v[140:141], v96
	v_cvt_pk_f32_fp8_sdwa v[142:143], v96 src0_sel:WORD_1
	v_fmac_f32_e32 v104, v30, v140
	v_fmac_f32_e32 v105, v30, v141
	v_fmac_f32_e32 v106, v30, v142
	v_fmac_f32_e32 v107, v30, v143
	v_cvt_pk_f32_fp8_e32 v[140:141], v97
	v_cvt_pk_f32_fp8_sdwa v[142:143], v97 src0_sel:WORD_1
	v_fmac_f32_e32 v108, v30, v140
	v_fmac_f32_e32 v109, v30, v141
	v_fmac_f32_e32 v110, v30, v142
	v_fmac_f32_e32 v111, v30, v143
	v_cvt_pk_f32_fp8_e32 v[140:141], v98
	v_cvt_pk_f32_fp8_sdwa v[142:143], v98 src0_sel:WORD_1
	v_fmac_f32_e32 v112, v30, v140
	v_fmac_f32_e32 v113, v30, v141
	v_fmac_f32_e32 v114, v30, v142
	v_fmac_f32_e32 v115, v30, v143
	v_cvt_pk_f32_fp8_e32 v[140:141], v99
	v_cvt_pk_f32_fp8_sdwa v[142:143], v99 src0_sel:WORD_1
	v_fmac_f32_e32 v116, v30, v140
	v_fmac_f32_e32 v117, v30, v141
	v_fmac_f32_e32 v118, v30, v142
	v_fmac_f32_e32 v119, v30, v143
	s_waitcnt vmcnt(10)
	v_cvt_pk_f32_fp8_e32 v[140:141], v100
	v_cvt_pk_f32_fp8_sdwa v[142:143], v100 src0_sel:WORD_1
	v_fmac_f32_e32 v104, v31, v140
	v_fmac_f32_e32 v105, v31, v141
	v_fmac_f32_e32 v106, v31, v142
	v_fmac_f32_e32 v107, v31, v143
	v_cvt_pk_f32_fp8_e32 v[140:141], v101
	v_cvt_pk_f32_fp8_sdwa v[142:143], v101 src0_sel:WORD_1
	v_fmac_f32_e32 v108, v31, v140
	v_fmac_f32_e32 v109, v31, v141
	v_fmac_f32_e32 v110, v31, v142
	v_fmac_f32_e32 v111, v31, v143
	v_cvt_pk_f32_fp8_e32 v[140:141], v102
	v_cvt_pk_f32_fp8_sdwa v[142:143], v102 src0_sel:WORD_1
	v_fmac_f32_e32 v112, v31, v140
	v_fmac_f32_e32 v113, v31, v141
	v_fmac_f32_e32 v114, v31, v142
	v_fmac_f32_e32 v115, v31, v143
	v_cvt_pk_f32_fp8_e32 v[140:141], v103
	v_cvt_pk_f32_fp8_sdwa v[142:143], v103 src0_sel:WORD_1
	v_fmac_f32_e32 v116, v31, v140
	v_fmac_f32_e32 v117, v31, v141
	v_fmac_f32_e32 v118, v31, v142
	v_fmac_f32_e32 v119, v31, v143
	global_load_dwordx4 v[72:75], v8, s[6:7]
	global_load_dwordx4 v[76:79], v9, s[6:7]
	global_load_dwordx4 v[80:83], v10, s[6:7]
	global_load_dwordx4 v[84:87], v11, s[6:7]
	global_load_dwordx4 v[88:91], v12, s[6:7]
	global_load_dwordx4 v[92:95], v13, s[6:7]
	global_load_dwordx4 v[96:99], v14, s[6:7]
	global_load_dwordx4 v[100:103], v15, s[6:7]
	s_waitcnt vmcnt(16)
	s_branch .Lq_vred
.Lq_vlast:
	s_waitcnt lgkmcnt(0)
	s_waitcnt vmcnt(17)
	v_cvt_pk_f32_fp8_e32 v[140:141], v40
	v_cvt_pk_f32_fp8_sdwa v[142:143], v40 src0_sel:WORD_1
	v_mul_f32_e32 v104, v16, v140
	v_mul_f32_e32 v105, v16, v141
	v_mul_f32_e32 v106, v16, v142
	v_mul_f32_e32 v107, v16, v143
	v_cvt_pk_f32_fp8_e32 v[140:141], v41
	v_cvt_pk_f32_fp8_sdwa v[142:143], v41 src0_sel:WORD_1
	v_mul_f32_e32 v108, v16, v140
	v_mul_f32_e32 v109, v16, v141
	v_mul_f32_e32 v110, v16, v142
	v_mul_f32_e32 v111, v16, v143
	v_cvt_pk_f32_fp8_e32 v[140:141], v42
	v_cvt_pk_f32_fp8_sdwa v[142:143], v42 src0_sel:WORD_1
	v_mul_f32_e32 v112, v16, v140
	v_mul_f32_e32 v113, v16, v141
	v_mul_f32_e32 v114, v16, v142
	v_mul_f32_e32 v115, v16, v143
	v_cvt_pk_f32_fp8_e32 v[140:141], v43
	v_cvt_pk_f32_fp8_sdwa v[142:143], v43 src0_sel:WORD_1
	v_mul_f32_e32 v116, v16, v140
	v_mul_f32_e32 v117, v16, v141
	v_mul_f32_e32 v118, v16, v142
	v_mul_f32_e32 v119, v16, v143
	s_waitcnt vmcnt(16)
	v_cvt_pk_f32_fp8_e32 v[140:141], v44
	v_cvt_pk_f32_fp8_sdwa v[142:143], v44 src0_sel:WORD_1
	v_fmac_f32_e32 v104, v17, v140
	v_fmac_f32_e32 v105, v17, v141
	v_fmac_f32_e32 v106, v17, v142
	v_fmac_f32_e32 v107, v17, v143
	v_cvt_pk_f32_fp8_e32 v[140:141], v45
	v_cvt_pk_f32_fp8_sdwa v[142:143], v45 src0_sel:WORD_1
	v_fmac_f32_e32 v108, v17, v140
	v_fmac_f32_e32 v109, v17, v141
	v_fmac_f32_e32 v110, v17, v142
	v_fmac_f32_e32 v111, v17, v143
	v_cvt_pk_f32_fp8_e32 v[140:141], v46
	v_cvt_pk_f32_fp8_sdwa v[142:143], v46 src0_sel:WORD_1
	v_fmac_f32_e32 v112, v17, v140
	v_fmac_f32_e32 v113, v17, v141
	v_fmac_f32_e32 v114, v17, v142
	v_fmac_f32_e32 v115, v17, v143
	v_cvt_pk_f32_fp8_e32 v[140:141], v47
	v_cvt_pk_f32_fp8_sdwa v[142:143], v47 src0_sel:WORD_1
	v_fmac_f32_e32 v116, v17, v140
	v_fmac_f32_e32 v117, v17, v141
	v_fmac_f32_e32 v118, v17, v142
	v_fmac_f32_e32 v119, v17, v143
	s_waitcnt vmcnt(15)
	v_cvt_pk_f32_fp8_e32 v[140:141], v48
	v_cvt_pk_f32_fp8_sdwa v[142:143], v48 src0_sel:WORD_1
	v_fmac_f32_e32 v104, v18, v140
	v_fmac_f32_e32 v105, v18, v141
	v_fmac_f32_e32 v106, v18, v142
	v_fmac_f32_e32 v107, v18, v143
	v_cvt_pk_f32_fp8_e32 v[140:141], v49
	v_cvt_pk_f32_fp8_sdwa v[142:143], v49 src0_sel:WORD_1
	v_fmac_f32_e32 v108, v18, v140
	v_fmac_f32_e32 v109, v18, v141
	v_fmac_f32_e32 v110, v18, v142
	v_fmac_f32_e32 v111, v18, v143
	v_cvt_pk_f32_fp8_e32 v[140:141], v50
	v_cvt_pk_f32_fp8_sdwa v[142:143], v50 src0_sel:WORD_1
	v_fmac_f32_e32 v112, v18, v140
	v_fmac_f32_e32 v113, v18, v141
	v_fmac_f32_e32 v114, v18, v142
	v_fmac_f32_e32 v115, v18, v143
	v_cvt_pk_f32_fp8_e32 v[140:141], v51
	v_cvt_pk_f32_fp8_sdwa v[142:143], v51 src0_sel:WORD_1
	v_fmac_f32_e32 v116, v18, v140
	v_fmac_f32_e32 v117, v18, v141
	v_fmac_f32_e32 v118, v18, v142
	v_fmac_f32_e32 v119, v18, v143
	s_waitcnt vmcnt(14)
	v_cvt_pk_f32_fp8_e32 v[140:141], v52
	v_cvt_pk_f32_fp8_sdwa v[142:143], v52 src0_sel:WORD_1
	v_fmac_f32_e32 v104, v19, v140
	v_fmac_f32_e32 v105, v19, v141
	v_fmac_f32_e32 v106, v19, v142
	v_fmac_f32_e32 v107, v19, v143
	v_cvt_pk_f32_fp8_e32 v[140:141], v53
	v_cvt_pk_f32_fp8_sdwa v[142:143], v53 src0_sel:WORD_1
	v_fmac_f32_e32 v108, v19, v140
	v_fmac_f32_e32 v109, v19, v141
	v_fmac_f32_e32 v110, v19, v142
	v_fmac_f32_e32 v111, v19, v143
	v_cvt_pk_f32_fp8_e32 v[140:141], v54
	v_cvt_pk_f32_fp8_sdwa v[142:143], v54 src0_sel:WORD_1
	v_fmac_f32_e32 v112, v19, v140
	v_fmac_f32_e32 v113, v19, v141
	v_fmac_f32_e32 v114, v19, v142
	v_fmac_f32_e32 v115, v19, v143
	v_cvt_pk_f32_fp8_e32 v[140:141], v55
	v_cvt_pk_f32_fp8_sdwa v[142:143], v55 src0_sel:WORD_1
	v_fmac_f32_e32 v116, v19, v140
	v_fmac_f32_e32 v117, v19, v141
	v_fmac_f32_e32 v118, v19, v142
	v_fmac_f32_e32 v119, v19, v143
	s_waitcnt vmcnt(13)
	v_cvt_pk_f32_fp8_e32 v[140:141], v56
	v_cvt_pk_f32_fp8_sdwa v[142:143], v56 src0_sel:WORD_1
	v_fmac_f32_e32 v104, v20, v140
	v_fmac_f32_e32 v105, v20, v141
	v_fmac_f32_e32 v106, v20, v142
	v_fmac_f32_e32 v107, v20, v143
	v_cvt_pk_f32_fp8_e32 v[140:141], v57
	v_cvt_pk_f32_fp8_sdwa v[142:143], v57 src0_sel:WORD_1
	v_fmac_f32_e32 v108, v20, v140
	v_fmac_f32_e32 v109, v20, v141
	v_fmac_f32_e32 v110, v20, v142
	v_fmac_f32_e32 v111, v20, v143
	v_cvt_pk_f32_fp8_e32 v[140:141], v58
	v_cvt_pk_f32_fp8_sdwa v[142:143], v58 src0_sel:WORD_1
	v_fmac_f32_e32 v112, v20, v140
	v_fmac_f32_e32 v113, v20, v141
	v_fmac_f32_e32 v114, v20, v142
	v_fmac_f32_e32 v115, v20, v143
	v_cvt_pk_f32_fp8_e32 v[140:141], v59
	v_cvt_pk_f32_fp8_sdwa v[142:143], v59 src0_sel:WORD_1
	v_fmac_f32_e32 v116, v20, v140
	v_fmac_f32_e32 v117, v20, v141
	v_fmac_f32_e32 v118, v20, v142
	v_fmac_f32_e32 v119, v20, v143
	s_waitcnt vmcnt(12)
	v_cvt_pk_f32_fp8_e32 v[140:141], v60
	v_cvt_pk_f32_fp8_sdwa v[142:143], v60 src0_sel:WORD_1
	v_fmac_f32_e32 v104, v21, v140
	v_fmac_f32_e32 v105, v21, v141
	v_fmac_f32_e32 v106, v21, v142
	v_fmac_f32_e32 v107, v21, v143
	v_cvt_pk_f32_fp8_e32 v[140:141], v61
	v_cvt_pk_f32_fp8_sdwa v[142:143], v61 src0_sel:WORD_1
	v_fmac_f32_e32 v108, v21, v140
	v_fmac_f32_e32 v109, v21, v141
	v_fmac_f32_e32 v110, v21, v142
	v_fmac_f32_e32 v111, v21, v143
	v_cvt_pk_f32_fp8_e32 v[140:141], v62
	v_cvt_pk_f32_fp8_sdwa v[142:143], v62 src0_sel:WORD_1
	v_fmac_f32_e32 v112, v21, v140
	v_fmac_f32_e32 v113, v21, v141
	v_fmac_f32_e32 v114, v21, v142
	v_fmac_f32_e32 v115, v21, v143
	v_cvt_pk_f32_fp8_e32 v[140:141], v63
	v_cvt_pk_f32_fp8_sdwa v[142:143], v63 src0_sel:WORD_1
	v_fmac_f32_e32 v116, v21, v140
	v_fmac_f32_e32 v117, v21, v141
	v_fmac_f32_e32 v118, v21, v142
	v_fmac_f32_e32 v119, v21, v143
	s_waitcnt vmcnt(11)
	v_cvt_pk_f32_fp8_e32 v[140:141], v64
	v_cvt_pk_f32_fp8_sdwa v[142:143], v64 src0_sel:WORD_1
	v_fmac_f32_e32 v104, v22, v140
	v_fmac_f32_e32 v105, v22, v141
	v_fmac_f32_e32 v106, v22, v142
	v_fmac_f32_e32 v107, v22, v143
	v_cvt_pk_f32_fp8_e32 v[140:141], v65
	v_cvt_pk_f32_fp8_sdwa v[142:143], v65 src0_sel:WORD_1
	v_fmac_f32_e32 v108, v22, v140
	v_fmac_f32_e32 v109, v22, v141
	v_fmac_f32_e32 v110, v22, v142
	v_fmac_f32_e32 v111, v22, v143
	v_cvt_pk_f32_fp8_e32 v[140:141], v66
	v_cvt_pk_f32_fp8_sdwa v[142:143], v66 src0_sel:WORD_1
	v_fmac_f32_e32 v112, v22, v140
	v_fmac_f32_e32 v113, v22, v141
	v_fmac_f32_e32 v114, v22, v142
	v_fmac_f32_e32 v115, v22, v143
	v_cvt_pk_f32_fp8_e32 v[140:141], v67
	v_cvt_pk_f32_fp8_sdwa v[142:143], v67 src0_sel:WORD_1
	v_fmac_f32_e32 v116, v22, v140
	v_fmac_f32_e32 v117, v22, v141
	v_fmac_f32_e32 v118, v22, v142
	v_fmac_f32_e32 v119, v22, v143
	s_waitcnt vmcnt(10)
	v_cvt_pk_f32_fp8_e32 v[140:141], v68
	v_cvt_pk_f32_fp8_sdwa v[142:143], v68 src0_sel:WORD_1
	v_fmac_f32_e32 v104, v23, v140
	v_fmac_f32_e32 v105, v23, v141
	v_fmac_f32_e32 v106, v23, v142
	v_fmac_f32_e32 v107, v23, v143
	v_cvt_pk_f32_fp8_e32 v[140:141], v69
	v_cvt_pk_f32_fp8_sdwa v[142:143], v69 src0_sel:WORD_1
	v_fmac_f32_e32 v108, v23, v140
	v_fmac_f32_e32 v109, v23, v141
	v_fmac_f32_e32 v110, v23, v142
	v_fmac_f32_e32 v111, v23, v143
	v_cvt_pk_f32_fp8_e32 v[140:141], v70
	v_cvt_pk_f32_fp8_sdwa v[142:143], v70 src0_sel:WORD_1
	v_fmac_f32_e32 v112, v23, v140
	v_fmac_f32_e32 v113, v23, v141
	v_fmac_f32_e32 v114, v23, v142
	v_fmac_f32_e32 v115, v23, v143
	v_cvt_pk_f32_fp8_e32 v[140:141], v71
	v_cvt_pk_f32_fp8_sdwa v[142:143], v71 src0_sel:WORD_1
	v_fmac_f32_e32 v116, v23, v140
	v_fmac_f32_e32 v117, v23, v141
	v_fmac_f32_e32 v118, v23, v142
	v_fmac_f32_e32 v119, v23, v143
	s_waitcnt vmcnt(9)
	v_cvt_pk_f32_fp8_e32 v[140:141], v72
	v_cvt_pk_f32_fp8_sdwa v[142:143], v72 src0_sel:WORD_1
	v_fmac_f32_e32 v104, v24, v140
	v_fmac_f32_e32 v105, v24, v141
	v_fmac_f32_e32 v106, v24, v142
	v_fmac_f32_e32 v107, v24, v143
	v_cvt_pk_f32_fp8_e32 v[140:141], v73
	v_cvt_pk_f32_fp8_sdwa v[142:143], v73 src0_sel:WORD_1
	v_fmac_f32_e32 v108, v24, v140
	v_fmac_f32_e32 v109, v24, v141
	v_fmac_f32_e32 v110, v24, v142
	v_fmac_f32_e32 v111, v24, v143
	v_cvt_pk_f32_fp8_e32 v[140:141], v74
	v_cvt_pk_f32_fp8_sdwa v[142:143], v74 src0_sel:WORD_1
	v_fmac_f32_e32 v112, v24, v140
	v_fmac_f32_e32 v113, v24, v141
	v_fmac_f32_e32 v114, v24, v142
	v_fmac_f32_e32 v115, v24, v143
	v_cvt_pk_f32_fp8_e32 v[140:141], v75
	v_cvt_pk_f32_fp8_sdwa v[142:143], v75 src0_sel:WORD_1
	v_fmac_f32_e32 v116, v24, v140
	v_fmac_f32_e32 v117, v24, v141
	v_fmac_f32_e32 v118, v24, v142
	v_fmac_f32_e32 v119, v24, v143
	s_waitcnt vmcnt(8)
	v_cvt_pk_f32_fp8_e32 v[140:141], v76
	v_cvt_pk_f32_fp8_sdwa v[142:143], v76 src0_sel:WORD_1
	v_fmac_f32_e32 v104, v25, v140
	v_fmac_f32_e32 v105, v25, v141
	v_fmac_f32_e32 v106, v25, v142
	v_fmac_f32_e32 v107, v25, v143
	v_cvt_pk_f32_fp8_e32 v[140:141], v77
	v_cvt_pk_f32_fp8_sdwa v[142:143], v77 src0_sel:WORD_1
	v_fmac_f32_e32 v108, v25, v140
	v_fmac_f32_e32 v109, v25, v141
	v_fmac_f32_e32 v110, v25, v142
	v_fmac_f32_e32 v111, v25, v143
	v_cvt_pk_f32_fp8_e32 v[140:141], v78
	v_cvt_pk_f32_fp8_sdwa v[142:143], v78 src0_sel:WORD_1
	v_fmac_f32_e32 v112, v25, v140
	v_fmac_f32_e32 v113, v25, v141
	v_fmac_f32_e32 v114, v25, v142
	v_fmac_f32_e32 v115, v25, v143
	v_cvt_pk_f32_fp8_e32 v[140:141], v79
	v_cvt_pk_f32_fp8_sdwa v[142:143], v79 src0_sel:WORD_1
	v_fmac_f32_e32 v116, v25, v140
	v_fmac_f32_e32 v117, v25, v141
	v_fmac_f32_e32 v118, v25, v142
	v_fmac_f32_e32 v119, v25, v143
	s_waitcnt vmcnt(7)
	v_cvt_pk_f32_fp8_e32 v[140:141], v80
	v_cvt_pk_f32_fp8_sdwa v[142:143], v80 src0_sel:WORD_1
	v_fmac_f32_e32 v104, v26, v140
	v_fmac_f32_e32 v105, v26, v141
	v_fmac_f32_e32 v106, v26, v142
	v_fmac_f32_e32 v107, v26, v143
	v_cvt_pk_f32_fp8_e32 v[140:141], v81
	v_cvt_pk_f32_fp8_sdwa v[142:143], v81 src0_sel:WORD_1
	v_fmac_f32_e32 v108, v26, v140
	v_fmac_f32_e32 v109, v26, v141
	v_fmac_f32_e32 v110, v26, v142
	v_fmac_f32_e32 v111, v26, v143
	v_cvt_pk_f32_fp8_e32 v[140:141], v82
	v_cvt_pk_f32_fp8_sdwa v[142:143], v82 src0_sel:WORD_1
	v_fmac_f32_e32 v112, v26, v140
	v_fmac_f32_e32 v113, v26, v141
	v_fmac_f32_e32 v114, v26, v142
	v_fmac_f32_e32 v115, v26, v143
	v_cvt_pk_f32_fp8_e32 v[140:141], v83
	v_cvt_pk_f32_fp8_sdwa v[142:143], v83 src0_sel:WORD_1
	v_fmac_f32_e32 v116, v26, v140
	v_fmac_f32_e32 v117, v26, v141
	v_fmac_f32_e32 v118, v26, v142
	v_fmac_f32_e32 v119, v26, v143
	s_waitcnt vmcnt(6)
	v_cvt_pk_f32_fp8_e32 v[140:141], v84
	v_cvt_pk_f32_fp8_sdwa v[142:143], v84 src0_sel:WORD_1
	v_fmac_f32_e32 v104, v27, v140
	v_fmac_f32_e32 v105, v27, v141
	v_fmac_f32_e32 v106, v27, v142
	v_fmac_f32_e32 v107, v27, v143
	v_cvt_pk_f32_fp8_e32 v[140:141], v85
	v_cvt_pk_f32_fp8_sdwa v[142:143], v85 src0_sel:WORD_1
	v_fmac_f32_e32 v108, v27, v140
	v_fmac_f32_e32 v109, v27, v141
	v_fmac_f32_e32 v110, v27, v142
	v_fmac_f32_e32 v111, v27, v143
	v_cvt_pk_f32_fp8_e32 v[140:141], v86
	v_cvt_pk_f32_fp8_sdwa v[142:143], v86 src0_sel:WORD_1
	v_fmac_f32_e32 v112, v27, v140
	v_fmac_f32_e32 v113, v27, v141
	v_fmac_f32_e32 v114, v27, v142
	v_fmac_f32_e32 v115, v27, v143
	v_cvt_pk_f32_fp8_e32 v[140:141], v87
	v_cvt_pk_f32_fp8_sdwa v[142:143], v87 src0_sel:WORD_1
	v_fmac_f32_e32 v116, v27, v140
	v_fmac_f32_e32 v117, v27, v141
	v_fmac_f32_e32 v118, v27, v142
	v_fmac_f32_e32 v119, v27, v143
	s_waitcnt vmcnt(5)
	v_cvt_pk_f32_fp8_e32 v[140:141], v88
	v_cvt_pk_f32_fp8_sdwa v[142:143], v88 src0_sel:WORD_1
	v_fmac_f32_e32 v104, v28, v140
	v_fmac_f32_e32 v105, v28, v141
	v_fmac_f32_e32 v106, v28, v142
	v_fmac_f32_e32 v107, v28, v143
	v_cvt_pk_f32_fp8_e32 v[140:141], v89
	v_cvt_pk_f32_fp8_sdwa v[142:143], v89 src0_sel:WORD_1
	v_fmac_f32_e32 v108, v28, v140
	v_fmac_f32_e32 v109, v28, v141
	v_fmac_f32_e32 v110, v28, v142
	v_fmac_f32_e32 v111, v28, v143
	v_cvt_pk_f32_fp8_e32 v[140:141], v90
	v_cvt_pk_f32_fp8_sdwa v[142:143], v90 src0_sel:WORD_1
	v_fmac_f32_e32 v112, v28, v140
	v_fmac_f32_e32 v113, v28, v141
	v_fmac_f32_e32 v114, v28, v142
	v_fmac_f32_e32 v115, v28, v143
	v_cvt_pk_f32_fp8_e32 v[140:141], v91
	v_cvt_pk_f32_fp8_sdwa v[142:143], v91 src0_sel:WORD_1
	v_fmac_f32_e32 v116, v28, v140
	v_fmac_f32_e32 v117, v28, v141
	v_fmac_f32_e32 v118, v28, v142
	v_fmac_f32_e32 v119, v28, v143
	s_waitcnt vmcnt(4)
	v_cvt_pk_f32_fp8_e32 v[140:141], v92
	v_cvt_pk_f32_fp8_sdwa v[142:143], v92 src0_sel:WORD_1
	v_fmac_f32_e32 v104, v29, v140
	v_fmac_f32_e32 v105, v29, v141
	v_fmac_f32_e32 v106, v29, v142
	v_fmac_f32_e32 v107, v29, v143
	v_cvt_pk_f32_fp8_e32 v[140:141], v93
	v_cvt_pk_f32_fp8_sdwa v[142:143], v93 src0_sel:WORD_1
	v_fmac_f32_e32 v108, v29, v140
	v_fmac_f32_e32 v109, v29, v141
	v_fmac_f32_e32 v110, v29, v142
	v_fmac_f32_e32 v111, v29, v143
	v_cvt_pk_f32_fp8_e32 v[140:141], v94
	v_cvt_pk_f32_fp8_sdwa v[142:143], v94 src0_sel:WORD_1
	v_fmac_f32_e32 v112, v29, v140
	v_fmac_f32_e32 v113, v29, v141
	v_fmac_f32_e32 v114, v29, v142
	v_fmac_f32_e32 v115, v29, v143
	v_cvt_pk_f32_fp8_e32 v[140:141], v95
	v_cvt_pk_f32_fp8_sdwa v[142:143], v95 src0_sel:WORD_1
	v_fmac_f32_e32 v116, v29, v140
	v_fmac_f32_e32 v117, v29, v141
	v_fmac_f32_e32 v118, v29, v142
	v_fmac_f32_e32 v119, v29, v143
	s_waitcnt vmcnt(3)
	v_cvt_pk_f32_fp8_e32 v[140:141], v96
	v_cvt_pk_f32_fp8_sdwa v[142:143], v96 src0_sel:WORD_1
	v_fmac_f32_e32 v104, v30, v140
	v_fmac_f32_e32 v105, v30, v141
	v_fmac_f32_e32 v106, v30, v142
	v_fmac_f32_e32 v107, v30, v143
	v_cvt_pk_f32_fp8_e32 v[140:141], v97
	v_cvt_pk_f32_fp8_sdwa v[142:143], v97 src0_sel:WORD_1
	v_fmac_f32_e32 v108, v30, v140
	v_fmac_f32_e32 v109, v30, v141
	v_fmac_f32_e32 v110, v30, v142
	v_fmac_f32_e32 v111, v30, v143
	v_cvt_pk_f32_fp8_e32 v[140:141], v98
	v_cvt_pk_f32_fp8_sdwa v[142:143], v98 src0_sel:WORD_1
	v_fmac_f32_e32 v112, v30, v140
	v_fmac_f32_e32 v113, v30, v141
	v_fmac_f32_e32 v114, v30, v142
	v_fmac_f32_e32 v115, v30, v143
	v_cvt_pk_f32_fp8_e32 v[140:141], v99
	v_cvt_pk_f32_fp8_sdwa v[142:143], v99 src0_sel:WORD_1
	v_fmac_f32_e32 v116, v30, v140
	v_fmac_f32_e32 v117, v30, v141
	v_fmac_f32_e32 v118, v30, v142
	v_fmac_f32_e32 v119, v30, v143
	s_waitcnt vmcnt(2)
	v_cvt_pk_f32_fp8_e32 v[140:141], v100
	v_cvt_pk_f32_fp8_sdwa v[142:143], v100 src0_sel:WORD_1
	v_fmac_f32_e32 v104, v31, v140
	v_fmac_f32_e32 v105, v31, v141
	v_fmac_f32_e32 v106, v31, v142
	v_fmac_f32_e32 v107, v31, v143
	v_cvt_pk_f32_fp8_e32 v[140:141], v101
	v_cvt_pk_f32_fp8_sdwa v[142:143], v101 src0_sel:WORD_1
	v_fmac_f32_e32 v108, v31, v140
	v_fmac_f32_e32 v109, v31, v141
	v_fmac_f32_e32 v110, v31, v142
	v_fmac_f32_e32 v111, v31, v143
	v_cvt_pk_f32_fp8_e32 v[140:141], v102
	v_cvt_pk_f32_fp8_sdwa v[142:143], v102 src0_sel:WORD_1
	v_fmac_f32_e32 v112, v31, v140
	v_fmac_f32_e32 v113, v31, v141
	v_fmac_f32_e32 v114, v31, v142
	v_fmac_f32_e32 v115, v31, v143
	v_cvt_pk_f32_fp8_e32 v[140:141], v103
	v_cvt_pk_f32_fp8_sdwa v[142:143], v103 src0_sel:WORD_1
	v_fmac_f32_e32 v116, v31, v140
	v_fmac_f32_e32 v117, v31, v141
	v_fmac_f32_e32 v118, v31, v142
	v_fmac_f32_e32 v119, v31, v143
	s_waitcnt vmcnt(0)
.Lq_vred:
	s_nop 1
	v_permlane32_swap_b32_e32 v104, v112
	v_permlane32_swap_b32_e32 v105, v113
	v_permlane32_swap_b32_e32 v106, v114
	v_permlane32_swap_b32_e32 v107, v115
	v_permlane32_swap_b32_e32 v108, v116
	v_permlane32_swap_b32_e32 v109, v117
	v_permlane32_swap_b32_e32 v110, v118
	v_permlane32_swap_b32_e32 v111, v119
	v_add_f32_e32 v104, v104, v112
	v_add_f32_e32 v105, v105, v113
	v_add_f32_e32 v106, v106, v114
	v_add_f32_e32 v107, v107, v115
	v_add_f32_e32 v108, v108, v116
	v_add_f32_e32 v109, v109, v117
	v_add_f32_e32 v110, v110, v118
	v_add_f32_e32 v111, v111, v119
	s_nop 1
	v_permlane16_swap_b32_e32 v104, v108
	v_permlane16_swap_b32_e32 v105, v109
	v_permlane16_swap_b32_e32 v106, v110
	v_permlane16_swap_b32_e32 v107, v111
	v_add_f32_e32 v104, v104, v108
	v_add_f32_e32 v105, v105, v109
	v_add_f32_e32 v106, v106, v110
	v_add_f32_e32 v107, v107, v111
	v_cndmask_b32_e64 v144, v104, v106, s[18:19]
	v_cndmask_b32_e64 v152, v106, v104, s[18:19]
	v_cndmask_b32_e64 v145, v105, v107, s[18:19]
	v_cndmask_b32_e64 v153, v107, v105, s[18:19]
	s_nop 1
	v_add_f32_dpp v104, v152, v144 row_ror:8 row_mask:0xf bank_mask:0xf
	v_add_f32_dpp v105, v153, v145 row_ror:8 row_mask:0xf bank_mask:0xf
	v_fmac_f32_e32 v124, v126, v104
	v_fmac_f32_e32 v125, v127, v105
	s_cmp_eq_u32 s3, 0
	s_cbranch_scc1 .Lq_vstx
	global_store_dwordx2 v199, v[124:125], s[10:11]
	s_branch .Lq_vnext

.Lq_vnext:
	s_add_i32 s14, s14, s26
	s_add_u32 s13, s13, 0x200
	s_add_u32 s100, s100, 1
	s_cmp_le_u32 s100, s12
	s_cbranch_scc1 .Lq_vtok
	s_add_i32 s8, s8, 1
	s_cmp_lt_u32 s8, 16
	s_cbranch_scc1 .Lq_vpass
	s_waitcnt vmcnt(0)
	s_cmp_lg_u32 s3, 0
	s_cbranch_scc1 .Lq_done
	v_mov_b32_e32 v0, 0x120a0
	ds_read_b64 v[0:1], v0
	s_waitcnt lgkmcnt(0)
	v_readfirstlane_b32 s4, v0
	v_readfirstlane_b32 s5, v1
	s_load_dwordx2 s[12:13], s[4:5], 0x30
	s_mov_b32 s14, s101
	s_add_i32 s5, s2, 1
	s_lshl_b32 s4, s5, 12
	s_mul_i32 s5, s5, 0x36000
	s_add_u32 s5, s5, 0x388e0000
	s_mov_b32 s21, 0x3a800000
	s_waitcnt lgkmcnt(0)
	s_add_u32 s12, s12, s4
	s_addc_u32 s13, s13, 0

.Lq_done:
	s_waitcnt vmcnt(0) lgkmcnt(0)
	v_readlane_b32 s18, v254, 14
	s_movk_i32 s19, 0x48
	v_readlane_b32 s20, v254, 12
	v_readlane_b32 s21, v254, 13
